# stack: + EpiResid residual loads batched under counted vmcnt, weight-transposer prefetch kept in flight, x f32->bf16 conversion unrolled 6 loads deep
# speedup vs baseline: 1.0662x; 1.0021x over previous
.LBB0_27:
	s_or_b64 exec, exec, s[4:5]
	v_or_b32_e32 v18, v67, v37
	v_ashrrev_i32_e32 v19, 31, v67
	v_ashrrev_i32_e32 v51, 31, v50
	v_or_b32_e32 v32, v67, v53
	v_mul_lo_u32 v20, v29, v18
	v_mul_lo_u32 v47, v28, v19
	v_mad_u64_u32 v[18:19], s[4:5], v28, v18, 0
	v_lshlrev_b64 v[30:31], 2, v[50:51]
	v_mul_lo_u32 v51, v29, v32
	v_mad_u64_u32 v[32:33], s[4:5], v28, v32, 0
	v_add3_u32 v19, v19, v47, v20
	v_or_b32_e32 v20, v67, v52
	v_add3_u32 v33, v33, v47, v51
	v_or_b32_e32 v51, v67, v54
	v_mul_lo_u32 v22, v29, v20
	v_mad_u64_u32 v[20:21], s[4:5], v28, v20, 0
	v_mul_lo_u32 v69, v29, v51
	v_mad_u64_u32 v[28:29], s[4:5], v28, v51, 0
	v_add3_u32 v21, v21, v47, v22
	v_add3_u32 v29, v29, v47, v69
	v_lshl_add_u64 v[18:19], v[18:19], 2, v[26:27]
	v_lshl_add_u64 v[20:21], v[20:21], 2, v[26:27]
	v_lshl_add_u64 v[32:33], v[32:33], 2, v[26:27]
	v_lshl_add_u64 v[26:27], v[28:29], 2, v[26:27]
	v_lshl_add_u64 v[18:19], v[18:19], 0, v[30:31]
	v_lshl_add_u64 v[20:21], v[20:21], 0, v[30:31]
	v_lshl_add_u64 v[32:33], v[32:33], 0, v[30:31]
	v_lshl_add_u64 v[26:27], v[26:27], 0, v[30:31]
	v_lshl_add_u64 v[18:19], v[18:19], 0, v[44:45]
	v_lshl_add_u64 v[22:23], v[20:21], 0, v[44:45]
	v_lshl_add_u64 v[32:33], v[32:33], 0, v[44:45]
	v_lshl_add_u64 v[30:31], v[26:27], 0, v[44:45]
	global_load_dwordx4 v[18:21], v[18:19], off
	s_nop 0
	global_load_dwordx4 v[22:25], v[22:23], off
	s_nop 0
	global_load_dwordx4 v[26:29], v[32:33], off
	s_nop 0
	global_load_dwordx4 v[30:33], v[30:31], off
	s_waitcnt vmcnt(4)
	s_branch .Ltr_go

.Ltr_go:
	ds_write2_b32 v61, v14, v15 offset1:1
	ds_write2_b32 v61, v16, v17 offset0:2 offset1:3
	v_add_u32_e32 v14, 0x1040, v61
	ds_write2_b32 v14, v10, v11 offset1:1
	v_add_u32_e32 v10, 0x1048, v61
	ds_write2_b32 v10, v12, v13 offset1:1
	v_add_u32_e32 v10, 0x2080, v61
	ds_write2_b32 v10, v6, v7 offset1:1
	v_add_u32_e32 v6, 0x2088, v61
	ds_write2_b32 v6, v8, v9 offset1:1
	v_add_u32_e32 v6, 0x30c0, v61
	ds_write2_b32 v6, v2, v3 offset1:1
	v_add_u32_e32 v2, 0x30c8, v61
	ds_write2_b32 v2, v4, v5 offset1:1
	v_add_u32_e32 v2, 0xc00, v55
	v_add_u32_e32 v4, 0xc00, v56
	s_waitcnt lgkmcnt(0)
	s_barrier
	ds_read2_b32 v[2:3], v2 offset0:12 offset1:142
	ds_read2_b32 v[4:5], v4 offset0:77 offset1:207
	v_add_u32_e32 v8, 0x400, v55
	ds_read2_b32 v[8:9], v8 offset0:4 offset1:134
	v_add_u32_e32 v6, 0x800, v56
	v_add_u32_e32 v10, 0x400, v56
	s_waitcnt lgkmcnt(1)
	v_cvt_pk_bf16_f32 v4, v2, v4
	v_add_u32_e32 v2, 0x800, v55
	v_cvt_pk_bf16_f32 v5, v3, v5
	ds_read2_b32 v[2:3], v2 offset0:8 offset1:138
	ds_read2_b32 v[6:7], v6 offset0:73 offset1:203
	ds_read2_b32 v[10:11], v10 offset0:69 offset1:199
	ds_read2_b32 v[12:13], v55 offset1:130
	ds_read2_b32 v[14:15], v56 offset0:65 offset1:195
	v_add_u32_e32 v16, v42, v43
	v_cmp_eq_u32_e32 vcc, 1, v35
	s_waitcnt lgkmcnt(2)
	v_cvt_pk_bf16_f32 v8, v8, v10
	v_lshlrev_b32_e32 v10, 1, v16
	v_and_b32_e32 v10, 0xffffffe0, v10
	v_lshl_add_u32 v10, v39, 4, v10
	v_and_or_b32 v10, v16, 15, v10
	v_cndmask_b32_e32 v10, v16, v10, vcc
	v_cvt_pk_bf16_f32 v3, v3, v7
	v_cvt_pk_bf16_f32 v9, v9, v11
	s_waitcnt lgkmcnt(0)
	v_cvt_pk_bf16_f32 v7, v13, v15
	v_ashrrev_i32_e32 v13, 31, v10
	v_mad_u64_u32 v[10:11], s[4:5], v10, v1, 0
	v_cvt_pk_bf16_f32 v2, v2, v6
	v_cvt_pk_bf16_f32 v6, v12, v14
	v_mov_b32_e32 v12, v11
	v_mad_u64_u32 v[12:13], s[4:5], v13, v1, v[12:13]
	v_mov_b32_e32 v11, v12
	v_lshl_add_u64 v[10:11], v[10:11], 1, v[40:41]
	v_ashrrev_i32_e32 v39, 31, v38
	v_lshl_add_u64 v[10:11], v[38:39], 1, v[10:11]
	v_mov_b32_e32 v47, v45
	v_lshl_add_u64 v[10:11], v[10:11], 0, v[46:47]
	flat_store_dwordx4 v[10:11], v[6:9]
	flat_store_dwordx4 v[10:11], v[2:5] offset:16
	v_add_u32_e32 v57, s2, v57
	v_add_u32_e32 v58, s3, v58
	v_add_u32_e32 v59, s11, v59
	v_add_u32_e32 v60, s33, v60
	s_andn2_b64 vcc, exec, s[22:23]
	v_mov_b32_e32 v39, v68
	v_mov_b32_e32 v35, v66
	v_mov_b32_e32 v42, v50
	v_mov_b32_e32 v38, v67
	v_mov_b64_e32 v[40:41], v[48:49]
	v_mov_b32_e32 v1, v65
	s_waitcnt vmcnt(2)
	v_mov_b64_e32 v[14:15], v[18:19]
	v_mov_b64_e32 v[16:17], v[20:21]
	v_mov_b64_e32 v[10:11], v[22:23]
	v_mov_b64_e32 v[12:13], v[24:25]
	v_mov_b64_e32 v[6:7], v[26:27]
	v_mov_b64_e32 v[8:9], v[28:29]
	v_mov_b64_e32 v[2:3], v[30:31]
	v_mov_b64_e32 v[4:5], v[32:33]
	s_waitcnt lgkmcnt(0)
	s_barrier
	s_cbranch_vccz .LBB0_50

.LBB0_50:
	s_load_dwordx16 s[56:71], s[0:1], 0x80
	s_ashr_i32 s11, s10, 31
	s_lshl_b64 s[2:3], s[10:11], 9
	v_ashrrev_i32_e32 v35, 31, v34
	v_lshl_add_u64 v[2:3], s[2:3], 0, v[34:35]
	s_waitcnt lgkmcnt(0)
	v_writelane_b32 v255, s56, 20
	s_ashr_i32 s35, s84, 31
	s_mov_b32 s34, s84
	v_writelane_b32 v255, s57, 21
	v_writelane_b32 v255, s58, 22
	v_writelane_b32 v255, s59, 23
	v_writelane_b32 v255, s60, 24
	v_writelane_b32 v255, s61, 25
	v_writelane_b32 v255, s62, 26
	v_writelane_b32 v255, s63, 27
	v_writelane_b32 v255, s64, 28
	v_writelane_b32 v255, s65, 29
	v_writelane_b32 v255, s66, 30
	v_writelane_b32 v255, s67, 31
	v_writelane_b32 v255, s68, 32
	v_writelane_b32 v255, s69, 33
	v_writelane_b32 v255, s70, 34
	v_writelane_b32 v255, s71, 35
	s_load_dwordx16 s[68:83], s[0:1], 0x0
	s_mov_b64 s[2:3], 0x840000
	s_lshl_b64 s[12:13], s[34:35], 9
	v_cmp_gt_u64_e32 vcc, s[2:3], v[2:3]
	s_and_saveexec_b64 s[4:5], vcc
	s_cbranch_execz .LBB0_53
	s_waitcnt lgkmcnt(0)
	s_cmp_lg_u32 s84, 0x100
	s_cbranch_scc1 .Lxc_orig
	v_lshlrev_b32_e32 v28, 4, v2
	v_lshlrev_b32_e32 v29, 3, v2
	s_mov_b64 s[98:99], s[68:69]
	s_add_u32 s100, s36, 0x44c4000
	s_addc_u32 s101, s37, 0
	global_load_dwordx4 v[4:7], v28, s[98:99]
	s_add_u32 s98, s98, 0x200000
	s_addc_u32 s99, s99, 0
	global_load_dwordx4 v[8:11], v28, s[98:99]
	s_add_u32 s98, s98, 0x200000
	s_addc_u32 s99, s99, 0
	global_load_dwordx4 v[12:15], v28, s[98:99]
	s_add_u32 s98, s98, 0x200000
	s_addc_u32 s99, s99, 0
	global_load_dwordx4 v[16:19], v28, s[98:99]
	s_add_u32 s98, s98, 0x200000
	s_addc_u32 s99, s99, 0
	global_load_dwordx4 v[20:23], v28, s[98:99]
	s_add_u32 s98, s98, 0x200000
	s_addc_u32 s99, s99, 0
	global_load_dwordx4 v[24:27], v28, s[98:99]
	s_waitcnt vmcnt(5)
	v_cvt_pk_bf16_f32 v4, v4, v5
	v_cvt_pk_bf16_f32 v5, v6, v7
	global_store_dwordx2 v29, v[4:5], s[100:101]
	s_add_u32 s98, s98, 0x200000
	s_addc_u32 s99, s99, 0
	global_load_dwordx4 v[4:7], v28, s[98:99]
	s_waitcnt vmcnt(6)
	v_cvt_pk_bf16_f32 v8, v8, v9
	v_cvt_pk_bf16_f32 v9, v10, v11
	s_add_u32 s100, s100, 0x100000
	s_addc_u32 s101, s101, 0
	global_store_dwordx2 v29, v[8:9], s[100:101]
	s_add_u32 s98, s98, 0x200000
	s_addc_u32 s99, s99, 0
	global_load_dwordx4 v[8:11], v28, s[98:99]
	s_waitcnt vmcnt(7)
	v_cvt_pk_bf16_f32 v12, v12, v13
	v_cvt_pk_bf16_f32 v13, v14, v15
	s_add_u32 s100, s100, 0x100000
	s_addc_u32 s101, s101, 0
	global_store_dwordx2 v29, v[12:13], s[100:101]
	s_add_u32 s98, s98, 0x200000
	s_addc_u32 s99, s99, 0
	global_load_dwordx4 v[12:15], v28, s[98:99]
	s_waitcnt vmcnt(8)
	v_cvt_pk_bf16_f32 v16, v16, v17
	v_cvt_pk_bf16_f32 v17, v18, v19
	s_add_u32 s100, s100, 0x100000
	s_addc_u32 s101, s101, 0
	global_store_dwordx2 v29, v[16:17], s[100:101]
	s_add_u32 s98, s98, 0x200000
	s_addc_u32 s99, s99, 0
	global_load_dwordx4 v[16:19], v28, s[98:99]
	s_waitcnt vmcnt(9)
	v_cvt_pk_bf16_f32 v20, v20, v21
	v_cvt_pk_bf16_f32 v21, v22, v23
	s_add_u32 s100, s100, 0x100000
	s_addc_u32 s101, s101, 0
	global_store_dwordx2 v29, v[20:21], s[100:101]
	s_add_u32 s98, s98, 0x200000
	s_addc_u32 s99, s99, 0
	global_load_dwordx4 v[20:23], v28, s[98:99]
	s_waitcnt vmcnt(10)
	v_cvt_pk_bf16_f32 v24, v24, v25
	v_cvt_pk_bf16_f32 v25, v26, v27
	s_add_u32 s100, s100, 0x100000
	s_addc_u32 s101, s101, 0
	global_store_dwordx2 v29, v[24:25], s[100:101]
	s_add_u32 s98, s98, 0x200000
	s_addc_u32 s99, s99, 0
	global_load_dwordx4 v[24:27], v28, s[98:99]
	s_waitcnt vmcnt(10)
	v_cvt_pk_bf16_f32 v4, v4, v5
	v_cvt_pk_bf16_f32 v5, v6, v7
	s_add_u32 s100, s100, 0x100000
	s_addc_u32 s101, s101, 0
	global_store_dwordx2 v29, v[4:5], s[100:101]
	s_add_u32 s98, s98, 0x200000
	s_addc_u32 s99, s99, 0
	global_load_dwordx4 v[4:7], v28, s[98:99]
	s_waitcnt vmcnt(10)
	v_cvt_pk_bf16_f32 v8, v8, v9
	v_cvt_pk_bf16_f32 v9, v10, v11
	s_add_u32 s100, s100, 0x100000
	s_addc_u32 s101, s101, 0
	global_store_dwordx2 v29, v[8:9], s[100:101]
	s_add_u32 s98, s98, 0x200000
	s_addc_u32 s99, s99, 0
	global_load_dwordx4 v[8:11], v28, s[98:99]
	s_waitcnt vmcnt(10)
	v_cvt_pk_bf16_f32 v12, v12, v13
	v_cvt_pk_bf16_f32 v13, v14, v15
	s_add_u32 s100, s100, 0x100000
	s_addc_u32 s101, s101, 0
	global_store_dwordx2 v29, v[12:13], s[100:101]
	s_add_u32 s98, s98, 0x200000
	s_addc_u32 s99, s99, 0
	global_load_dwordx4 v[12:15], v28, s[98:99]
	s_waitcnt vmcnt(10)
	v_cvt_pk_bf16_f32 v16, v16, v17
	v_cvt_pk_bf16_f32 v17, v18, v19
	s_add_u32 s100, s100, 0x100000
	s_addc_u32 s101, s101, 0
	global_store_dwordx2 v29, v[16:17], s[100:101]
	s_add_u32 s98, s98, 0x200000
	s_addc_u32 s99, s99, 0
	global_load_dwordx4 v[16:19], v28, s[98:99]
	s_waitcnt vmcnt(10)
	v_cvt_pk_bf16_f32 v20, v20, v21
	v_cvt_pk_bf16_f32 v21, v22, v23
	s_add_u32 s100, s100, 0x100000
	s_addc_u32 s101, s101, 0
	global_store_dwordx2 v29, v[20:21], s[100:101]
	s_add_u32 s98, s98, 0x200000
	s_addc_u32 s99, s99, 0
	global_load_dwordx4 v[20:23], v28, s[98:99]
	s_waitcnt vmcnt(10)
	v_cvt_pk_bf16_f32 v24, v24, v25
	v_cvt_pk_bf16_f32 v25, v26, v27
	s_add_u32 s100, s100, 0x100000
	s_addc_u32 s101, s101, 0
	global_store_dwordx2 v29, v[24:25], s[100:101]
	s_add_u32 s98, s98, 0x200000
	s_addc_u32 s99, s99, 0
	global_load_dwordx4 v[24:27], v28, s[98:99]
	s_waitcnt vmcnt(10)
	v_cvt_pk_bf16_f32 v4, v4, v5
	v_cvt_pk_bf16_f32 v5, v6, v7
	s_add_u32 s100, s100, 0x100000
	s_addc_u32 s101, s101, 0
	global_store_dwordx2 v29, v[4:5], s[100:101]
	s_add_u32 s98, s98, 0x200000
	s_addc_u32 s99, s99, 0
	global_load_dwordx4 v[4:7], v28, s[98:99]
	s_waitcnt vmcnt(10)
	v_cvt_pk_bf16_f32 v8, v8, v9
	v_cvt_pk_bf16_f32 v9, v10, v11
	s_add_u32 s100, s100, 0x100000
	s_addc_u32 s101, s101, 0
	global_store_dwordx2 v29, v[8:9], s[100:101]
	s_add_u32 s98, s98, 0x200000
	s_addc_u32 s99, s99, 0
	global_load_dwordx4 v[8:11], v28, s[98:99]
	s_waitcnt vmcnt(10)
	v_cvt_pk_bf16_f32 v12, v12, v13
	v_cvt_pk_bf16_f32 v13, v14, v15
	s_add_u32 s100, s100, 0x100000
	s_addc_u32 s101, s101, 0
	global_store_dwordx2 v29, v[12:13], s[100:101]
	s_add_u32 s98, s98, 0x200000
	s_addc_u32 s99, s99, 0
	global_load_dwordx4 v[12:15], v28, s[98:99]
	s_waitcnt vmcnt(10)
	v_cvt_pk_bf16_f32 v16, v16, v17
	v_cvt_pk_bf16_f32 v17, v18, v19
	s_add_u32 s100, s100, 0x100000
	s_addc_u32 s101, s101, 0
	global_store_dwordx2 v29, v[16:17], s[100:101]
	s_add_u32 s98, s98, 0x200000
	s_addc_u32 s99, s99, 0
	global_load_dwordx4 v[16:19], v28, s[98:99]
	s_waitcnt vmcnt(10)
	v_cvt_pk_bf16_f32 v20, v20, v21
	v_cvt_pk_bf16_f32 v21, v22, v23
	s_add_u32 s100, s100, 0x100000
	s_addc_u32 s101, s101, 0
	global_store_dwordx2 v29, v[20:21], s[100:101]
	s_add_u32 s98, s98, 0x200000
	s_addc_u32 s99, s99, 0
	global_load_dwordx4 v[20:23], v28, s[98:99]
	s_waitcnt vmcnt(10)
	v_cvt_pk_bf16_f32 v24, v24, v25
	v_cvt_pk_bf16_f32 v25, v26, v27
	s_add_u32 s100, s100, 0x100000
	s_addc_u32 s101, s101, 0
	global_store_dwordx2 v29, v[24:25], s[100:101]
	s_add_u32 s98, s98, 0x200000
	s_addc_u32 s99, s99, 0
	global_load_dwordx4 v[24:27], v28, s[98:99]
	s_waitcnt vmcnt(10)
	v_cvt_pk_bf16_f32 v4, v4, v5
	v_cvt_pk_bf16_f32 v5, v6, v7
	s_add_u32 s100, s100, 0x100000
	s_addc_u32 s101, s101, 0
	global_store_dwordx2 v29, v[4:5], s[100:101]
	s_add_u32 s98, s98, 0x200000
	s_addc_u32 s99, s99, 0
	global_load_dwordx4 v[4:7], v28, s[98:99]
	s_waitcnt vmcnt(10)
	v_cvt_pk_bf16_f32 v8, v8, v9
	v_cvt_pk_bf16_f32 v9, v10, v11
	s_add_u32 s100, s100, 0x100000
	s_addc_u32 s101, s101, 0
	global_store_dwordx2 v29, v[8:9], s[100:101]
	s_add_u32 s98, s98, 0x200000
	s_addc_u32 s99, s99, 0
	global_load_dwordx4 v[8:11], v28, s[98:99]
	s_waitcnt vmcnt(10)
	v_cvt_pk_bf16_f32 v12, v12, v13
	v_cvt_pk_bf16_f32 v13, v14, v15
	s_add_u32 s100, s100, 0x100000
	s_addc_u32 s101, s101, 0
	global_store_dwordx2 v29, v[12:13], s[100:101]
	s_add_u32 s98, s98, 0x200000
	s_addc_u32 s99, s99, 0
	global_load_dwordx4 v[12:15], v28, s[98:99]
	s_waitcnt vmcnt(10)
	v_cvt_pk_bf16_f32 v16, v16, v17
	v_cvt_pk_bf16_f32 v17, v18, v19
	s_add_u32 s100, s100, 0x100000
	s_addc_u32 s101, s101, 0
	global_store_dwordx2 v29, v[16:17], s[100:101]
	s_add_u32 s98, s98, 0x200000
	s_addc_u32 s99, s99, 0
	global_load_dwordx4 v[16:19], v28, s[98:99]
	s_waitcnt vmcnt(10)
	v_cvt_pk_bf16_f32 v20, v20, v21
	v_cvt_pk_bf16_f32 v21, v22, v23
	s_add_u32 s100, s100, 0x100000
	s_addc_u32 s101, s101, 0
	global_store_dwordx2 v29, v[20:21], s[100:101]
	s_add_u32 s98, s98, 0x200000
	s_addc_u32 s99, s99, 0
	global_load_dwordx4 v[20:23], v28, s[98:99]
	s_waitcnt vmcnt(10)
	v_cvt_pk_bf16_f32 v24, v24, v25
	v_cvt_pk_bf16_f32 v25, v26, v27
	s_add_u32 s100, s100, 0x100000
	s_addc_u32 s101, s101, 0
	global_store_dwordx2 v29, v[24:25], s[100:101]
	s_add_u32 s98, s98, 0x200000
	s_addc_u32 s99, s99, 0
	global_load_dwordx4 v[24:27], v28, s[98:99]
	s_waitcnt vmcnt(10)
	v_cvt_pk_bf16_f32 v4, v4, v5
	v_cvt_pk_bf16_f32 v5, v6, v7
	s_add_u32 s100, s100, 0x100000
	s_addc_u32 s101, s101, 0
	global_store_dwordx2 v29, v[4:5], s[100:101]
	s_add_u32 s98, s98, 0x200000
	s_addc_u32 s99, s99, 0
	global_load_dwordx4 v[4:7], v28, s[98:99]
	s_waitcnt vmcnt(10)
	v_cvt_pk_bf16_f32 v8, v8, v9
	v_cvt_pk_bf16_f32 v9, v10, v11
	s_add_u32 s100, s100, 0x100000
	s_addc_u32 s101, s101, 0
	global_store_dwordx2 v29, v[8:9], s[100:101]
	s_add_u32 s98, s98, 0x200000
	s_addc_u32 s99, s99, 0
	global_load_dwordx4 v[8:11], v28, s[98:99]
	s_waitcnt vmcnt(10)
	v_cvt_pk_bf16_f32 v12, v12, v13
	v_cvt_pk_bf16_f32 v13, v14, v15
	s_add_u32 s100, s100, 0x100000
	s_addc_u32 s101, s101, 0
	global_store_dwordx2 v29, v[12:13], s[100:101]
	s_add_u32 s98, s98, 0x200000
	s_addc_u32 s99, s99, 0
	global_load_dwordx4 v[12:15], v28, s[98:99]
	s_waitcnt vmcnt(10)
	v_cvt_pk_bf16_f32 v16, v16, v17
	v_cvt_pk_bf16_f32 v17, v18, v19
	s_add_u32 s100, s100, 0x100000
	s_addc_u32 s101, s101, 0
	global_store_dwordx2 v29, v[16:17], s[100:101]
	s_add_u32 s98, s98, 0x200000
	s_addc_u32 s99, s99, 0
	global_load_dwordx4 v[16:19], v28, s[98:99]
	s_waitcnt vmcnt(10)
	v_cvt_pk_bf16_f32 v20, v20, v21
	v_cvt_pk_bf16_f32 v21, v22, v23
	s_add_u32 s100, s100, 0x100000
	s_addc_u32 s101, s101, 0
	global_store_dwordx2 v29, v[20:21], s[100:101]
	s_add_u32 s98, s98, 0x200000
	s_addc_u32 s99, s99, 0
	global_load_dwordx4 v[20:23], v28, s[98:99]
	s_waitcnt vmcnt(10)
	v_cvt_pk_bf16_f32 v24, v24, v25
	v_cvt_pk_bf16_f32 v25, v26, v27
	s_add_u32 s100, s100, 0x100000
	s_addc_u32 s101, s101, 0
	global_store_dwordx2 v29, v[24:25], s[100:101]
	s_add_u32 s98, s98, 0x200000
	s_addc_u32 s99, s99, 0
	global_load_dwordx4 v[24:27], v28, s[98:99]
	s_waitcnt vmcnt(10)
	v_cvt_pk_bf16_f32 v4, v4, v5
	v_cvt_pk_bf16_f32 v5, v6, v7
	s_add_u32 s100, s100, 0x100000
	s_addc_u32 s101, s101, 0
	global_store_dwordx2 v29, v[4:5], s[100:101]
	s_add_u32 s98, s98, 0x200000
	s_addc_u32 s99, s99, 0
	global_load_dwordx4 v[4:7], v28, s[98:99]
	s_waitcnt vmcnt(10)
	v_cvt_pk_bf16_f32 v8, v8, v9
	v_cvt_pk_bf16_f32 v9, v10, v11
	s_add_u32 s100, s100, 0x100000
	s_addc_u32 s101, s101, 0
	global_store_dwordx2 v29, v[8:9], s[100:101]
	s_add_u32 s98, s98, 0x200000
	s_addc_u32 s99, s99, 0
	global_load_dwordx4 v[8:11], v28, s[98:99]
	s_waitcnt vmcnt(10)
	v_cvt_pk_bf16_f32 v12, v12, v13
	v_cvt_pk_bf16_f32 v13, v14, v15
	s_add_u32 s100, s100, 0x100000
	s_addc_u32 s101, s101, 0
	global_store_dwordx2 v29, v[12:13], s[100:101]
	s_add_u32 s98, s98, 0x200000
	s_addc_u32 s99, s99, 0
	global_load_dwordx4 v[12:15], v28, s[98:99]
	s_waitcnt vmcnt(10)
	v_cvt_pk_bf16_f32 v16, v16, v17
	v_cvt_pk_bf16_f32 v17, v18, v19
	s_add_u32 s100, s100, 0x100000
	s_addc_u32 s101, s101, 0
	global_store_dwordx2 v29, v[16:17], s[100:101]
	s_add_u32 s98, s98, 0x200000
	s_addc_u32 s99, s99, 0
	global_load_dwordx4 v[16:19], v28, s[98:99]
	s_waitcnt vmcnt(10)
	v_cvt_pk_bf16_f32 v20, v20, v21
	v_cvt_pk_bf16_f32 v21, v22, v23
	s_add_u32 s100, s100, 0x100000
	s_addc_u32 s101, s101, 0
	global_store_dwordx2 v29, v[20:21], s[100:101]
	s_add_u32 s98, s98, 0x200000
	s_addc_u32 s99, s99, 0
	global_load_dwordx4 v[20:23], v28, s[98:99]
	s_waitcnt vmcnt(10)
	v_cvt_pk_bf16_f32 v24, v24, v25
	v_cvt_pk_bf16_f32 v25, v26, v27
	s_add_u32 s100, s100, 0x100000
	s_addc_u32 s101, s101, 0
	global_store_dwordx2 v29, v[24:25], s[100:101]
	s_add_u32 s98, s98, 0x200000
	s_addc_u32 s99, s99, 0
	global_load_dwordx4 v[24:27], v28, s[98:99]
	s_waitcnt vmcnt(10)
	v_cvt_pk_bf16_f32 v4, v4, v5
	v_cvt_pk_bf16_f32 v5, v6, v7
	s_add_u32 s100, s100, 0x100000
	s_addc_u32 s101, s101, 0
	global_store_dwordx2 v29, v[4:5], s[100:101]
	s_add_u32 s98, s98, 0x200000
	s_addc_u32 s99, s99, 0
	global_load_dwordx4 v[4:7], v28, s[98:99]
	s_waitcnt vmcnt(10)
	v_cvt_pk_bf16_f32 v8, v8, v9
	v_cvt_pk_bf16_f32 v9, v10, v11
	s_add_u32 s100, s100, 0x100000
	s_addc_u32 s101, s101, 0
	global_store_dwordx2 v29, v[8:9], s[100:101]
	s_add_u32 s98, s98, 0x200000
	s_addc_u32 s99, s99, 0
	global_load_dwordx4 v[8:11], v28, s[98:99]
	s_waitcnt vmcnt(10)
	v_cvt_pk_bf16_f32 v12, v12, v13
	v_cvt_pk_bf16_f32 v13, v14, v15
	s_add_u32 s100, s100, 0x100000
	s_addc_u32 s101, s101, 0
	global_store_dwordx2 v29, v[12:13], s[100:101]
	s_add_u32 s98, s98, 0x200000
	s_addc_u32 s99, s99, 0
	global_load_dwordx4 v[12:15], v28, s[98:99]
	s_waitcnt vmcnt(10)
	v_cvt_pk_bf16_f32 v16, v16, v17
	v_cvt_pk_bf16_f32 v17, v18, v19
	s_add_u32 s100, s100, 0x100000
	s_addc_u32 s101, s101, 0
	global_store_dwordx2 v29, v[16:17], s[100:101]
	s_add_u32 s98, s98, 0x200000
	s_addc_u32 s99, s99, 0
	global_load_dwordx4 v[16:19], v28, s[98:99]
	s_waitcnt vmcnt(10)
	v_cvt_pk_bf16_f32 v20, v20, v21
	v_cvt_pk_bf16_f32 v21, v22, v23
	s_add_u32 s100, s100, 0x100000
	s_addc_u32 s101, s101, 0
	global_store_dwordx2 v29, v[20:21], s[100:101]
	s_add_u32 s98, s98, 0x200000
	s_addc_u32 s99, s99, 0
	global_load_dwordx4 v[20:23], v28, s[98:99]
	s_waitcnt vmcnt(10)
	v_cvt_pk_bf16_f32 v24, v24, v25
	v_cvt_pk_bf16_f32 v25, v26, v27
	s_add_u32 s100, s100, 0x100000
	s_addc_u32 s101, s101, 0
	global_store_dwordx2 v29, v[24:25], s[100:101]
	s_add_u32 s98, s98, 0x200000
	s_addc_u32 s99, s99, 0
	global_load_dwordx4 v[24:27], v28, s[98:99]
	s_waitcnt vmcnt(10)
	v_cvt_pk_bf16_f32 v4, v4, v5
	v_cvt_pk_bf16_f32 v5, v6, v7
	s_add_u32 s100, s100, 0x100000
	s_addc_u32 s101, s101, 0
	global_store_dwordx2 v29, v[4:5], s[100:101]
	s_add_u32 s98, s98, 0x200000
	s_addc_u32 s99, s99, 0
	global_load_dwordx4 v[4:7], v28, s[98:99]
	s_waitcnt vmcnt(10)
	v_cvt_pk_bf16_f32 v8, v8, v9
	v_cvt_pk_bf16_f32 v9, v10, v11
	s_add_u32 s100, s100, 0x100000
	s_addc_u32 s101, s101, 0
	global_store_dwordx2 v29, v[8:9], s[100:101]
	s_add_u32 s98, s98, 0x200000
	s_addc_u32 s99, s99, 0
	global_load_dwordx4 v[8:11], v28, s[98:99]
	s_waitcnt vmcnt(10)
	v_cvt_pk_bf16_f32 v12, v12, v13
	v_cvt_pk_bf16_f32 v13, v14, v15
	s_add_u32 s100, s100, 0x100000
	s_addc_u32 s101, s101, 0
	global_store_dwordx2 v29, v[12:13], s[100:101]
	s_add_u32 s98, s98, 0x200000
	s_addc_u32 s99, s99, 0
	global_load_dwordx4 v[12:15], v28, s[98:99]
	s_waitcnt vmcnt(10)
	v_cvt_pk_bf16_f32 v16, v16, v17
	v_cvt_pk_bf16_f32 v17, v18, v19
	s_add_u32 s100, s100, 0x100000
	s_addc_u32 s101, s101, 0
	global_store_dwordx2 v29, v[16:17], s[100:101]
	s_add_u32 s98, s98, 0x200000
	s_addc_u32 s99, s99, 0
	global_load_dwordx4 v[16:19], v28, s[98:99]
	s_waitcnt vmcnt(10)
	v_cvt_pk_bf16_f32 v20, v20, v21
	v_cvt_pk_bf16_f32 v21, v22, v23
	s_add_u32 s100, s100, 0x100000
	s_addc_u32 s101, s101, 0
	global_store_dwordx2 v29, v[20:21], s[100:101]
	s_add_u32 s98, s98, 0x200000
	s_addc_u32 s99, s99, 0
	global_load_dwordx4 v[20:23], v28, s[98:99]
	s_waitcnt vmcnt(10)
	v_cvt_pk_bf16_f32 v24, v24, v25
	v_cvt_pk_bf16_f32 v25, v26, v27
	s_add_u32 s100, s100, 0x100000
	s_addc_u32 s101, s101, 0
	global_store_dwordx2 v29, v[24:25], s[100:101]
	s_add_u32 s98, s98, 0x200000
	s_addc_u32 s99, s99, 0
	global_load_dwordx4 v[24:27], v28, s[98:99]
	s_waitcnt vmcnt(10)
	v_cvt_pk_bf16_f32 v4, v4, v5
	v_cvt_pk_bf16_f32 v5, v6, v7
	s_add_u32 s100, s100, 0x100000
	s_addc_u32 s101, s101, 0
	global_store_dwordx2 v29, v[4:5], s[100:101]
	s_add_u32 s98, s98, 0x200000
	s_addc_u32 s99, s99, 0
	global_load_dwordx4 v[4:7], v28, s[98:99]
	s_waitcnt vmcnt(10)
	v_cvt_pk_bf16_f32 v8, v8, v9
	v_cvt_pk_bf16_f32 v9, v10, v11
	s_add_u32 s100, s100, 0x100000
	s_addc_u32 s101, s101, 0
	global_store_dwordx2 v29, v[8:9], s[100:101]
	s_add_u32 s98, s98, 0x200000
	s_addc_u32 s99, s99, 0
	global_load_dwordx4 v[8:11], v28, s[98:99]
	s_waitcnt vmcnt(10)
	v_cvt_pk_bf16_f32 v12, v12, v13
	v_cvt_pk_bf16_f32 v13, v14, v15
	s_add_u32 s100, s100, 0x100000
	s_addc_u32 s101, s101, 0
	global_store_dwordx2 v29, v[12:13], s[100:101]
	s_add_u32 s98, s98, 0x200000
	s_addc_u32 s99, s99, 0
	global_load_dwordx4 v[12:15], v28, s[98:99]
	s_waitcnt vmcnt(10)
	v_cvt_pk_bf16_f32 v16, v16, v17
	v_cvt_pk_bf16_f32 v17, v18, v19
	s_add_u32 s100, s100, 0x100000
	s_addc_u32 s101, s101, 0
	global_store_dwordx2 v29, v[16:17], s[100:101]
	s_add_u32 s98, s98, 0x200000
	s_addc_u32 s99, s99, 0
	global_load_dwordx4 v[16:19], v28, s[98:99]
	s_waitcnt vmcnt(10)
	v_cvt_pk_bf16_f32 v20, v20, v21
	v_cvt_pk_bf16_f32 v21, v22, v23
	s_add_u32 s100, s100, 0x100000
	s_addc_u32 s101, s101, 0
	global_store_dwordx2 v29, v[20:21], s[100:101]
	s_add_u32 s98, s98, 0x200000
	s_addc_u32 s99, s99, 0
	global_load_dwordx4 v[20:23], v28, s[98:99]
	s_waitcnt vmcnt(10)
	v_cvt_pk_bf16_f32 v24, v24, v25
	v_cvt_pk_bf16_f32 v25, v26, v27
	s_add_u32 s100, s100, 0x100000
	s_addc_u32 s101, s101, 0
	global_store_dwordx2 v29, v[24:25], s[100:101]
	s_add_u32 s98, s98, 0x200000
	s_addc_u32 s99, s99, 0
	global_load_dwordx4 v[24:27], v28, s[98:99]
	s_waitcnt vmcnt(10)
	v_cvt_pk_bf16_f32 v4, v4, v5
	v_cvt_pk_bf16_f32 v5, v6, v7
	s_add_u32 s100, s100, 0x100000
	s_addc_u32 s101, s101, 0
	global_store_dwordx2 v29, v[4:5], s[100:101]
	s_add_u32 s98, s98, 0x200000
	s_addc_u32 s99, s99, 0
	global_load_dwordx4 v[4:7], v28, s[98:99]
	s_waitcnt vmcnt(10)
	v_cvt_pk_bf16_f32 v8, v8, v9
	v_cvt_pk_bf16_f32 v9, v10, v11
	s_add_u32 s100, s100, 0x100000
	s_addc_u32 s101, s101, 0
	global_store_dwordx2 v29, v[8:9], s[100:101]
	s_add_u32 s98, s98, 0x200000
	s_addc_u32 s99, s99, 0
	global_load_dwordx4 v[8:11], v28, s[98:99]
	s_waitcnt vmcnt(10)
	v_cvt_pk_bf16_f32 v12, v12, v13
	v_cvt_pk_bf16_f32 v13, v14, v15
	s_add_u32 s100, s100, 0x100000
	s_addc_u32 s101, s101, 0
	global_store_dwordx2 v29, v[12:13], s[100:101]
	s_add_u32 s98, s98, 0x200000
	s_addc_u32 s99, s99, 0
	global_load_dwordx4 v[12:15], v28, s[98:99]
	s_waitcnt vmcnt(10)
	v_cvt_pk_bf16_f32 v16, v16, v17
	v_cvt_pk_bf16_f32 v17, v18, v19
	s_add_u32 s100, s100, 0x100000
	s_addc_u32 s101, s101, 0
	global_store_dwordx2 v29, v[16:17], s[100:101]
	s_add_u32 s98, s98, 0x200000
	s_addc_u32 s99, s99, 0
	global_load_dwordx4 v[16:19], v28, s[98:99]
	s_waitcnt vmcnt(10)
	v_cvt_pk_bf16_f32 v20, v20, v21
	v_cvt_pk_bf16_f32 v21, v22, v23
	s_add_u32 s100, s100, 0x100000
	s_addc_u32 s101, s101, 0
	global_store_dwordx2 v29, v[20:21], s[100:101]
	s_mov_b64 s[98:99], s[70:71]
	global_load_dwordx4 v[20:23], v28, s[98:99]
	s_waitcnt vmcnt(10)
	v_cvt_pk_bf16_f32 v24, v24, v25
	v_cvt_pk_bf16_f32 v25, v26, v27
	s_add_u32 s100, s100, 0x100000
	s_addc_u32 s101, s101, 0
	global_store_dwordx2 v29, v[24:25], s[100:101]
	s_add_u32 s98, s98, 0x200000
	s_addc_u32 s99, s99, 0
	global_load_dwordx4 v[24:27], v28, s[98:99]
	s_waitcnt vmcnt(10)
	v_cvt_pk_bf16_f32 v4, v4, v5
	v_cvt_pk_bf16_f32 v5, v6, v7
	s_add_u32 s100, s100, 0x100000
	s_addc_u32 s101, s101, 0
	global_store_dwordx2 v29, v[4:5], s[100:101]
	s_waitcnt vmcnt(9)
	v_cvt_pk_bf16_f32 v8, v8, v9
	v_cvt_pk_bf16_f32 v9, v10, v11
	s_add_u32 s100, s100, 0x100000
	s_addc_u32 s101, s101, 0
	global_store_dwordx2 v29, v[8:9], s[100:101]
	s_waitcnt vmcnt(8)
	v_cvt_pk_bf16_f32 v12, v12, v13
	v_cvt_pk_bf16_f32 v13, v14, v15
	s_add_u32 s100, s100, 0x100000
	s_addc_u32 s101, s101, 0
	global_store_dwordx2 v29, v[12:13], s[100:101]
	s_waitcnt vmcnt(7)
	v_cvt_pk_bf16_f32 v16, v16, v17
	v_cvt_pk_bf16_f32 v17, v18, v19
	s_add_u32 s100, s100, 0x100000
	s_addc_u32 s101, s101, 0
	global_store_dwordx2 v29, v[16:17], s[100:101]
	s_waitcnt vmcnt(6)
	v_cvt_pk_bf16_f32 v20, v20, v21
	v_cvt_pk_bf16_f32 v21, v22, v23
	s_add_u32 s100, s100, 0x100000
	s_addc_u32 s101, s101, 0
	global_store_dwordx2 v29, v[20:21], s[100:101]
	s_waitcnt vmcnt(5)
	v_cvt_pk_bf16_f32 v24, v24, v25
	v_cvt_pk_bf16_f32 v25, v26, v27
	s_add_u32 s100, s100, 0x100000
	s_addc_u32 s101, s101, 0
	global_store_dwordx2 v29, v[24:25], s[100:101]
	s_branch .LBB0_53
.Lxc_orig:
	s_add_u32 s6, s70, 0xf8000000
	s_addc_u32 s7, s71, -1
	s_lshl_b64 s[2:3], s[10:11], 13
	v_lshl_add_u64 v[4:5], v[34:35], 4, s[2:3]
	s_lshl_b64 s[14:15], s[34:35], 13
	s_lshl_b64 s[2:3], s[10:11], 12
	s_add_u32 s2, s8, s2
	s_addc_u32 s3, s9, s3
	v_lshl_add_u64 v[6:7], v[34:35], 3, s[2:3]
	s_mov_b64 s[2:3], 0x44c4004
	v_lshl_add_u64 v[6:7], v[6:7], 0, s[2:3]
	s_lshl_b64 s[16:17], s[34:35], 12
	s_mov_b64 s[18:19], 0
	s_mov_b64 s[20:21], 0x800000
	s_mov_b64 s[22:23], 0x83ffff
	v_mov_b64_e32 v[8:9], v[2:3]

.LBB0_568:
	s_or_b64 exec, exec, s[44:45]
	s_lshl_b32 s98, s40, 1
	s_lshl_b32 s99, s42, 11
	s_add_i32 s98, s98, s99
	v_lshlrev_b32_e32 v132, 6, v146
	v_lshl_add_u32 v132, v147, 3, v132
	v_lshl_add_u32 v132, v148, 11, v132
	v_lshl_add_u32 v132, v145, 17, v132
	v_add_u32_e32 v132, s98, v132
	v_add_u32_e32 v133, 0x8000, v132
	v_add_u32_e32 v134, 0x10000, v132
	v_add_u32_e32 v135, 0x18000, v132
	v_add_u32_e32 v136, 0x40000, v132
	v_add_u32_e32 v137, 0x48000, v132
	v_add_u32_e32 v138, 0x50000, v132
	v_add_u32_e32 v139, 0x58000, v132
	global_load_dwordx2 v[176:177], v132, s[6:7]
	global_load_dwordx2 v[178:179], v132, s[6:7] offset:32
	global_load_dwordx2 v[180:181], v133, s[6:7]
	global_load_dwordx2 v[182:183], v133, s[6:7] offset:32
	global_load_dwordx2 v[184:185], v134, s[6:7]
	global_load_dwordx2 v[186:187], v134, s[6:7] offset:32
	global_load_dwordx2 v[188:189], v135, s[6:7]
	global_load_dwordx2 v[190:191], v135, s[6:7] offset:32
	global_load_dwordx2 v[192:193], v132, s[6:7] offset:256
	global_load_dwordx2 v[194:195], v132, s[6:7] offset:288
	global_load_dwordx2 v[196:197], v133, s[6:7] offset:256
	global_load_dwordx2 v[198:199], v133, s[6:7] offset:288
	global_load_dwordx2 v[200:201], v134, s[6:7] offset:256
	global_load_dwordx2 v[202:203], v134, s[6:7] offset:288
	global_load_dwordx2 v[204:205], v135, s[6:7] offset:256
	global_load_dwordx2 v[206:207], v135, s[6:7] offset:288
	global_load_dwordx2 v[208:209], v136, s[6:7]
	global_load_dwordx2 v[210:211], v136, s[6:7] offset:32
	global_load_dwordx2 v[212:213], v137, s[6:7]
	global_load_dwordx2 v[214:215], v137, s[6:7] offset:32
	global_load_dwordx2 v[216:217], v138, s[6:7]
	global_load_dwordx2 v[218:219], v138, s[6:7] offset:32
	global_load_dwordx2 v[220:221], v139, s[6:7]
	global_load_dwordx2 v[222:223], v139, s[6:7] offset:32
	global_load_dwordx2 v[224:225], v136, s[6:7] offset:256
	global_load_dwordx2 v[226:227], v136, s[6:7] offset:288
	global_load_dwordx2 v[228:229], v137, s[6:7] offset:256
	global_load_dwordx2 v[230:231], v137, s[6:7] offset:288
	global_load_dwordx2 v[232:233], v138, s[6:7] offset:256
	global_load_dwordx2 v[234:235], v138, s[6:7] offset:288
	global_load_dwordx2 v[236:237], v139, s[6:7] offset:256
	global_load_dwordx2 v[238:239], v139, s[6:7] offset:288
	s_waitcnt vmcnt(30)
	v_lshlrev_b32_e32 v140, 16, v177
	v_and_b32_e32 v141, 0xffff0000, v177
	v_and_b32_e32 v177, 0xffff0000, v176
	v_lshlrev_b32_e32 v176, 16, v176
	v_lshlrev_b32_e32 v142, 16, v179
	v_and_b32_e32 v143, 0xffff0000, v179
	v_and_b32_e32 v179, 0xffff0000, v178
	v_lshlrev_b32_e32 v178, 16, v178
	v_pk_fma_f32 v[124:125], v[176:177], s[38:39], v[124:125] op_sel_hi:[1,0,1]
	v_pk_fma_f32 v[126:127], v[140:141], s[38:39], v[126:127] op_sel_hi:[1,0,1]
	v_pk_fma_f32 v[120:121], v[178:179], s[38:39], v[120:121] op_sel_hi:[1,0,1]
	v_pk_fma_f32 v[122:123], v[142:143], s[38:39], v[122:123] op_sel_hi:[1,0,1]
	v_cvt_pk_bf16_f32 v124, v124, v125
	v_cvt_pk_bf16_f32 v125, v126, v127
	v_cvt_pk_bf16_f32 v120, v120, v121
	v_cvt_pk_bf16_f32 v121, v122, v123
	global_store_dwordx2 v132, v[124:125], s[8:9]
	global_store_dwordx2 v132, v[120:121], s[8:9] offset:32
	s_waitcnt vmcnt(30)
	v_lshlrev_b32_e32 v140, 16, v181
	v_and_b32_e32 v141, 0xffff0000, v181
	v_and_b32_e32 v181, 0xffff0000, v180
	v_lshlrev_b32_e32 v180, 16, v180
	v_lshlrev_b32_e32 v142, 16, v183
	v_and_b32_e32 v143, 0xffff0000, v183
	v_and_b32_e32 v183, 0xffff0000, v182
	v_lshlrev_b32_e32 v182, 16, v182
	v_pk_fma_f32 v[112:113], v[180:181], s[38:39], v[112:113] op_sel_hi:[1,0,1]
	v_pk_fma_f32 v[114:115], v[140:141], s[38:39], v[114:115] op_sel_hi:[1,0,1]
	v_pk_fma_f32 v[116:117], v[182:183], s[38:39], v[116:117] op_sel_hi:[1,0,1]
	v_pk_fma_f32 v[118:119], v[142:143], s[38:39], v[118:119] op_sel_hi:[1,0,1]
	v_cvt_pk_bf16_f32 v112, v112, v113
	v_cvt_pk_bf16_f32 v113, v114, v115
	v_cvt_pk_bf16_f32 v116, v116, v117
	v_cvt_pk_bf16_f32 v117, v118, v119
	global_store_dwordx2 v133, v[112:113], s[8:9]
	global_store_dwordx2 v133, v[116:117], s[8:9] offset:32
	s_waitcnt vmcnt(30)
	v_lshlrev_b32_e32 v140, 16, v185
	v_and_b32_e32 v141, 0xffff0000, v185
	v_and_b32_e32 v185, 0xffff0000, v184
	v_lshlrev_b32_e32 v184, 16, v184
	v_lshlrev_b32_e32 v142, 16, v187
	v_and_b32_e32 v143, 0xffff0000, v187
	v_and_b32_e32 v187, 0xffff0000, v186
	v_lshlrev_b32_e32 v186, 16, v186
	v_pk_fma_f32 v[104:105], v[184:185], s[38:39], v[104:105] op_sel_hi:[1,0,1]
	v_pk_fma_f32 v[106:107], v[140:141], s[38:39], v[106:107] op_sel_hi:[1,0,1]
	v_pk_fma_f32 v[108:109], v[186:187], s[38:39], v[108:109] op_sel_hi:[1,0,1]
	v_pk_fma_f32 v[110:111], v[142:143], s[38:39], v[110:111] op_sel_hi:[1,0,1]
	v_cvt_pk_bf16_f32 v104, v104, v105
	v_cvt_pk_bf16_f32 v105, v106, v107
	v_cvt_pk_bf16_f32 v108, v108, v109
	v_cvt_pk_bf16_f32 v109, v110, v111
	global_store_dwordx2 v134, v[104:105], s[8:9]
	global_store_dwordx2 v134, v[108:109], s[8:9] offset:32
	s_waitcnt vmcnt(30)
	v_lshlrev_b32_e32 v140, 16, v189
	v_and_b32_e32 v141, 0xffff0000, v189
	v_and_b32_e32 v189, 0xffff0000, v188
	v_lshlrev_b32_e32 v188, 16, v188
	v_lshlrev_b32_e32 v142, 16, v191
	v_and_b32_e32 v143, 0xffff0000, v191
	v_and_b32_e32 v191, 0xffff0000, v190
	v_lshlrev_b32_e32 v190, 16, v190
	v_pk_fma_f32 v[96:97], v[188:189], s[38:39], v[96:97] op_sel_hi:[1,0,1]
	v_pk_fma_f32 v[98:99], v[140:141], s[38:39], v[98:99] op_sel_hi:[1,0,1]
	v_pk_fma_f32 v[100:101], v[190:191], s[38:39], v[100:101] op_sel_hi:[1,0,1]
	v_pk_fma_f32 v[102:103], v[142:143], s[38:39], v[102:103] op_sel_hi:[1,0,1]
	v_cvt_pk_bf16_f32 v96, v96, v97
	v_cvt_pk_bf16_f32 v97, v98, v99
	v_cvt_pk_bf16_f32 v100, v100, v101
	v_cvt_pk_bf16_f32 v101, v102, v103
	global_store_dwordx2 v135, v[96:97], s[8:9]
	global_store_dwordx2 v135, v[100:101], s[8:9] offset:32
	s_waitcnt vmcnt(30)
	v_lshlrev_b32_e32 v140, 16, v193
	v_and_b32_e32 v141, 0xffff0000, v193
	v_and_b32_e32 v193, 0xffff0000, v192
	v_lshlrev_b32_e32 v192, 16, v192
	v_lshlrev_b32_e32 v142, 16, v195
	v_and_b32_e32 v143, 0xffff0000, v195
	v_and_b32_e32 v195, 0xffff0000, v194
	v_lshlrev_b32_e32 v194, 16, v194
	v_pk_fma_f32 v[92:93], v[192:193], s[38:39], v[92:93] op_sel_hi:[1,0,1]
	v_pk_fma_f32 v[94:95], v[140:141], s[38:39], v[94:95] op_sel_hi:[1,0,1]
	v_pk_fma_f32 v[88:89], v[194:195], s[38:39], v[88:89] op_sel_hi:[1,0,1]
	v_pk_fma_f32 v[90:91], v[142:143], s[38:39], v[90:91] op_sel_hi:[1,0,1]
	v_cvt_pk_bf16_f32 v92, v92, v93
	v_cvt_pk_bf16_f32 v93, v94, v95
	v_cvt_pk_bf16_f32 v88, v88, v89
	v_cvt_pk_bf16_f32 v89, v90, v91
	global_store_dwordx2 v132, v[92:93], s[8:9] offset:256
	global_store_dwordx2 v132, v[88:89], s[8:9] offset:288
	s_waitcnt vmcnt(30)
	v_lshlrev_b32_e32 v140, 16, v197
	v_and_b32_e32 v141, 0xffff0000, v197
	v_and_b32_e32 v197, 0xffff0000, v196
	v_lshlrev_b32_e32 v196, 16, v196
	v_lshlrev_b32_e32 v142, 16, v199
	v_and_b32_e32 v143, 0xffff0000, v199
	v_and_b32_e32 v199, 0xffff0000, v198
	v_lshlrev_b32_e32 v198, 16, v198
	v_pk_fma_f32 v[80:81], v[196:197], s[38:39], v[80:81] op_sel_hi:[1,0,1]
	v_pk_fma_f32 v[82:83], v[140:141], s[38:39], v[82:83] op_sel_hi:[1,0,1]
	v_pk_fma_f32 v[84:85], v[198:199], s[38:39], v[84:85] op_sel_hi:[1,0,1]
	v_pk_fma_f32 v[86:87], v[142:143], s[38:39], v[86:87] op_sel_hi:[1,0,1]
	v_cvt_pk_bf16_f32 v80, v80, v81
	v_cvt_pk_bf16_f32 v81, v82, v83
	v_cvt_pk_bf16_f32 v84, v84, v85
	v_cvt_pk_bf16_f32 v85, v86, v87
	global_store_dwordx2 v133, v[80:81], s[8:9] offset:256
	global_store_dwordx2 v133, v[84:85], s[8:9] offset:288
	s_waitcnt vmcnt(30)
	v_lshlrev_b32_e32 v140, 16, v201
	v_and_b32_e32 v141, 0xffff0000, v201
	v_and_b32_e32 v201, 0xffff0000, v200
	v_lshlrev_b32_e32 v200, 16, v200
	v_lshlrev_b32_e32 v142, 16, v203
	v_and_b32_e32 v143, 0xffff0000, v203
	v_and_b32_e32 v203, 0xffff0000, v202
	v_lshlrev_b32_e32 v202, 16, v202
	v_pk_fma_f32 v[72:73], v[200:201], s[38:39], v[72:73] op_sel_hi:[1,0,1]
	v_pk_fma_f32 v[74:75], v[140:141], s[38:39], v[74:75] op_sel_hi:[1,0,1]
	v_pk_fma_f32 v[76:77], v[202:203], s[38:39], v[76:77] op_sel_hi:[1,0,1]
	v_pk_fma_f32 v[78:79], v[142:143], s[38:39], v[78:79] op_sel_hi:[1,0,1]
	v_cvt_pk_bf16_f32 v72, v72, v73
	v_cvt_pk_bf16_f32 v73, v74, v75
	v_cvt_pk_bf16_f32 v76, v76, v77
	v_cvt_pk_bf16_f32 v77, v78, v79
	global_store_dwordx2 v134, v[72:73], s[8:9] offset:256
	global_store_dwordx2 v134, v[76:77], s[8:9] offset:288
	s_waitcnt vmcnt(30)
	v_lshlrev_b32_e32 v140, 16, v205
	v_and_b32_e32 v141, 0xffff0000, v205
	v_and_b32_e32 v205, 0xffff0000, v204
	v_lshlrev_b32_e32 v204, 16, v204
	v_lshlrev_b32_e32 v142, 16, v207
	v_and_b32_e32 v143, 0xffff0000, v207
	v_and_b32_e32 v207, 0xffff0000, v206
	v_lshlrev_b32_e32 v206, 16, v206
	v_pk_fma_f32 v[64:65], v[204:205], s[38:39], v[64:65] op_sel_hi:[1,0,1]
	v_pk_fma_f32 v[66:67], v[140:141], s[38:39], v[66:67] op_sel_hi:[1,0,1]
	v_pk_fma_f32 v[68:69], v[206:207], s[38:39], v[68:69] op_sel_hi:[1,0,1]
	v_pk_fma_f32 v[70:71], v[142:143], s[38:39], v[70:71] op_sel_hi:[1,0,1]
	v_cvt_pk_bf16_f32 v64, v64, v65
	v_cvt_pk_bf16_f32 v65, v66, v67
	v_cvt_pk_bf16_f32 v68, v68, v69
	v_cvt_pk_bf16_f32 v69, v70, v71
	global_store_dwordx2 v135, v[64:65], s[8:9] offset:256
	global_store_dwordx2 v135, v[68:69], s[8:9] offset:288
	s_waitcnt vmcnt(30)
	v_lshlrev_b32_e32 v140, 16, v209
	v_and_b32_e32 v141, 0xffff0000, v209
	v_and_b32_e32 v209, 0xffff0000, v208
	v_lshlrev_b32_e32 v208, 16, v208
	v_lshlrev_b32_e32 v142, 16, v211
	v_and_b32_e32 v143, 0xffff0000, v211
	v_and_b32_e32 v211, 0xffff0000, v210
	v_lshlrev_b32_e32 v210, 16, v210
	v_pk_fma_f32 v[60:61], v[208:209], s[38:39], v[60:61] op_sel_hi:[1,0,1]
	v_pk_fma_f32 v[62:63], v[140:141], s[38:39], v[62:63] op_sel_hi:[1,0,1]
	v_pk_fma_f32 v[56:57], v[210:211], s[38:39], v[56:57] op_sel_hi:[1,0,1]
	v_pk_fma_f32 v[58:59], v[142:143], s[38:39], v[58:59] op_sel_hi:[1,0,1]
	v_cvt_pk_bf16_f32 v60, v60, v61
	v_cvt_pk_bf16_f32 v61, v62, v63
	v_cvt_pk_bf16_f32 v56, v56, v57
	v_cvt_pk_bf16_f32 v57, v58, v59
	global_store_dwordx2 v136, v[60:61], s[8:9]
	global_store_dwordx2 v136, v[56:57], s[8:9] offset:32
	s_waitcnt vmcnt(30)
	v_lshlrev_b32_e32 v140, 16, v213
	v_and_b32_e32 v141, 0xffff0000, v213
	v_and_b32_e32 v213, 0xffff0000, v212
	v_lshlrev_b32_e32 v212, 16, v212
	v_lshlrev_b32_e32 v142, 16, v215
	v_and_b32_e32 v143, 0xffff0000, v215
	v_and_b32_e32 v215, 0xffff0000, v214
	v_lshlrev_b32_e32 v214, 16, v214
	v_pk_fma_f32 v[48:49], v[212:213], s[38:39], v[48:49] op_sel_hi:[1,0,1]
	v_pk_fma_f32 v[50:51], v[140:141], s[38:39], v[50:51] op_sel_hi:[1,0,1]
	v_pk_fma_f32 v[52:53], v[214:215], s[38:39], v[52:53] op_sel_hi:[1,0,1]
	v_pk_fma_f32 v[54:55], v[142:143], s[38:39], v[54:55] op_sel_hi:[1,0,1]
	v_cvt_pk_bf16_f32 v48, v48, v49
	v_cvt_pk_bf16_f32 v49, v50, v51
	v_cvt_pk_bf16_f32 v52, v52, v53
	v_cvt_pk_bf16_f32 v53, v54, v55
	global_store_dwordx2 v137, v[48:49], s[8:9]
	global_store_dwordx2 v137, v[52:53], s[8:9] offset:32
	s_waitcnt vmcnt(30)
	v_lshlrev_b32_e32 v140, 16, v217
	v_and_b32_e32 v141, 0xffff0000, v217
	v_and_b32_e32 v217, 0xffff0000, v216
	v_lshlrev_b32_e32 v216, 16, v216
	v_lshlrev_b32_e32 v142, 16, v219
	v_and_b32_e32 v143, 0xffff0000, v219
	v_and_b32_e32 v219, 0xffff0000, v218
	v_lshlrev_b32_e32 v218, 16, v218
	v_pk_fma_f32 v[40:41], v[216:217], s[38:39], v[40:41] op_sel_hi:[1,0,1]
	v_pk_fma_f32 v[42:43], v[140:141], s[38:39], v[42:43] op_sel_hi:[1,0,1]
	v_pk_fma_f32 v[44:45], v[218:219], s[38:39], v[44:45] op_sel_hi:[1,0,1]
	v_pk_fma_f32 v[46:47], v[142:143], s[38:39], v[46:47] op_sel_hi:[1,0,1]
	v_cvt_pk_bf16_f32 v40, v40, v41
	v_cvt_pk_bf16_f32 v41, v42, v43
	v_cvt_pk_bf16_f32 v44, v44, v45
	v_cvt_pk_bf16_f32 v45, v46, v47
	global_store_dwordx2 v138, v[40:41], s[8:9]
	global_store_dwordx2 v138, v[44:45], s[8:9] offset:32
	s_waitcnt vmcnt(30)
	v_lshlrev_b32_e32 v140, 16, v221
	v_and_b32_e32 v141, 0xffff0000, v221
	v_and_b32_e32 v221, 0xffff0000, v220
	v_lshlrev_b32_e32 v220, 16, v220
	v_lshlrev_b32_e32 v142, 16, v223
	v_and_b32_e32 v143, 0xffff0000, v223
	v_and_b32_e32 v223, 0xffff0000, v222
	v_lshlrev_b32_e32 v222, 16, v222
	v_pk_fma_f32 v[32:33], v[220:221], s[38:39], v[32:33] op_sel_hi:[1,0,1]
	v_pk_fma_f32 v[34:35], v[140:141], s[38:39], v[34:35] op_sel_hi:[1,0,1]
	v_pk_fma_f32 v[36:37], v[222:223], s[38:39], v[36:37] op_sel_hi:[1,0,1]
	v_pk_fma_f32 v[38:39], v[142:143], s[38:39], v[38:39] op_sel_hi:[1,0,1]
	v_cvt_pk_bf16_f32 v32, v32, v33
	v_cvt_pk_bf16_f32 v33, v34, v35
	v_cvt_pk_bf16_f32 v36, v36, v37
	v_cvt_pk_bf16_f32 v37, v38, v39
	global_store_dwordx2 v139, v[32:33], s[8:9]
	global_store_dwordx2 v139, v[36:37], s[8:9] offset:32
	s_waitcnt vmcnt(30)
	v_lshlrev_b32_e32 v140, 16, v225
	v_and_b32_e32 v141, 0xffff0000, v225
	v_and_b32_e32 v225, 0xffff0000, v224
	v_lshlrev_b32_e32 v224, 16, v224
	v_lshlrev_b32_e32 v142, 16, v227
	v_and_b32_e32 v143, 0xffff0000, v227
	v_and_b32_e32 v227, 0xffff0000, v226
	v_lshlrev_b32_e32 v226, 16, v226
	v_pk_fma_f32 v[28:29], v[224:225], s[38:39], v[28:29] op_sel_hi:[1,0,1]
	v_pk_fma_f32 v[30:31], v[140:141], s[38:39], v[30:31] op_sel_hi:[1,0,1]
	v_pk_fma_f32 v[24:25], v[226:227], s[38:39], v[24:25] op_sel_hi:[1,0,1]
	v_pk_fma_f32 v[26:27], v[142:143], s[38:39], v[26:27] op_sel_hi:[1,0,1]
	v_cvt_pk_bf16_f32 v28, v28, v29
	v_cvt_pk_bf16_f32 v29, v30, v31
	v_cvt_pk_bf16_f32 v24, v24, v25
	v_cvt_pk_bf16_f32 v25, v26, v27
	global_store_dwordx2 v136, v[28:29], s[8:9] offset:256
	global_store_dwordx2 v136, v[24:25], s[8:9] offset:288
	s_waitcnt vmcnt(30)
	v_lshlrev_b32_e32 v140, 16, v229
	v_and_b32_e32 v141, 0xffff0000, v229
	v_and_b32_e32 v229, 0xffff0000, v228
	v_lshlrev_b32_e32 v228, 16, v228
	v_lshlrev_b32_e32 v142, 16, v231
	v_and_b32_e32 v143, 0xffff0000, v231
	v_and_b32_e32 v231, 0xffff0000, v230
	v_lshlrev_b32_e32 v230, 16, v230
	v_pk_fma_f32 v[16:17], v[228:229], s[38:39], v[16:17] op_sel_hi:[1,0,1]
	v_pk_fma_f32 v[18:19], v[140:141], s[38:39], v[18:19] op_sel_hi:[1,0,1]
	v_pk_fma_f32 v[20:21], v[230:231], s[38:39], v[20:21] op_sel_hi:[1,0,1]
	v_pk_fma_f32 v[22:23], v[142:143], s[38:39], v[22:23] op_sel_hi:[1,0,1]
	v_cvt_pk_bf16_f32 v16, v16, v17
	v_cvt_pk_bf16_f32 v17, v18, v19
	v_cvt_pk_bf16_f32 v20, v20, v21
	v_cvt_pk_bf16_f32 v21, v22, v23
	global_store_dwordx2 v137, v[16:17], s[8:9] offset:256
	global_store_dwordx2 v137, v[20:21], s[8:9] offset:288
	s_waitcnt vmcnt(30)
	v_lshlrev_b32_e32 v140, 16, v233
	v_and_b32_e32 v141, 0xffff0000, v233
	v_and_b32_e32 v233, 0xffff0000, v232
	v_lshlrev_b32_e32 v232, 16, v232
	v_lshlrev_b32_e32 v142, 16, v235
	v_and_b32_e32 v143, 0xffff0000, v235
	v_and_b32_e32 v235, 0xffff0000, v234
	v_lshlrev_b32_e32 v234, 16, v234
	v_pk_fma_f32 v[8:9], v[232:233], s[38:39], v[8:9] op_sel_hi:[1,0,1]
	v_pk_fma_f32 v[10:11], v[140:141], s[38:39], v[10:11] op_sel_hi:[1,0,1]
	v_pk_fma_f32 v[12:13], v[234:235], s[38:39], v[12:13] op_sel_hi:[1,0,1]
	v_pk_fma_f32 v[14:15], v[142:143], s[38:39], v[14:15] op_sel_hi:[1,0,1]
	v_cvt_pk_bf16_f32 v8, v8, v9
	v_cvt_pk_bf16_f32 v9, v10, v11
	v_cvt_pk_bf16_f32 v12, v12, v13
	v_cvt_pk_bf16_f32 v13, v14, v15
	global_store_dwordx2 v138, v[8:9], s[8:9] offset:256
	global_store_dwordx2 v138, v[12:13], s[8:9] offset:288
	s_waitcnt vmcnt(30)
	v_lshlrev_b32_e32 v140, 16, v237
	v_and_b32_e32 v141, 0xffff0000, v237
	v_and_b32_e32 v237, 0xffff0000, v236
	v_lshlrev_b32_e32 v236, 16, v236
	v_lshlrev_b32_e32 v142, 16, v239
	v_and_b32_e32 v143, 0xffff0000, v239
	v_and_b32_e32 v239, 0xffff0000, v238
	v_lshlrev_b32_e32 v238, 16, v238
	v_pk_fma_f32 v[0:1], v[236:237], s[38:39], v[0:1] op_sel_hi:[1,0,1]
	v_pk_fma_f32 v[2:3], v[140:141], s[38:39], v[2:3] op_sel_hi:[1,0,1]
	v_pk_fma_f32 v[4:5], v[238:239], s[38:39], v[4:5] op_sel_hi:[1,0,1]
	v_pk_fma_f32 v[6:7], v[142:143], s[38:39], v[6:7] op_sel_hi:[1,0,1]
	v_cvt_pk_bf16_f32 v0, v0, v1
	v_cvt_pk_bf16_f32 v1, v2, v3
	v_cvt_pk_bf16_f32 v4, v4, v5
	v_cvt_pk_bf16_f32 v5, v6, v7
	global_store_dwordx2 v139, v[0:1], s[8:9] offset:256
	global_store_dwordx2 v139, v[4:5], s[8:9] offset:288
	s_andn2_b64 vcc, exec, s[0:1]
	s_mov_b32 s43, s61
	s_mov_b32 s42, s62
	s_cbranch_vccz .LBB0_577

.LBB0_749:
	s_or_b64 exec, exec, s[38:39]
	s_lshl_b32 s98, s61, 1
	s_lshl_b32 s99, s62, 11
	s_add_i32 s98, s98, s99
	v_lshlrev_b32_e32 v132, 6, v150
	v_lshl_add_u32 v132, v151, 3, v132
	v_lshl_add_u32 v132, v152, 11, v132
	v_lshl_add_u32 v132, v149, 17, v132
	v_add_u32_e32 v132, s98, v132
	v_add_u32_e32 v133, 0x8000, v132
	v_add_u32_e32 v134, 0x10000, v132
	v_add_u32_e32 v135, 0x18000, v132
	v_add_u32_e32 v136, 0x40000, v132
	v_add_u32_e32 v137, 0x48000, v132
	v_add_u32_e32 v138, 0x50000, v132
	v_add_u32_e32 v139, 0x58000, v132
	global_load_dwordx2 v[180:181], v132, s[8:9]
	global_load_dwordx2 v[182:183], v132, s[8:9] offset:32
	global_load_dwordx2 v[184:185], v133, s[8:9]
	global_load_dwordx2 v[186:187], v133, s[8:9] offset:32
	global_load_dwordx2 v[188:189], v134, s[8:9]
	global_load_dwordx2 v[190:191], v134, s[8:9] offset:32
	global_load_dwordx2 v[192:193], v135, s[8:9]
	global_load_dwordx2 v[194:195], v135, s[8:9] offset:32
	global_load_dwordx2 v[196:197], v132, s[8:9] offset:256
	global_load_dwordx2 v[198:199], v132, s[8:9] offset:288
	global_load_dwordx2 v[200:201], v133, s[8:9] offset:256
	global_load_dwordx2 v[202:203], v133, s[8:9] offset:288
	global_load_dwordx2 v[204:205], v134, s[8:9] offset:256
	global_load_dwordx2 v[206:207], v134, s[8:9] offset:288
	global_load_dwordx2 v[208:209], v135, s[8:9] offset:256
	global_load_dwordx2 v[210:211], v135, s[8:9] offset:288
	global_load_dwordx2 v[212:213], v136, s[8:9]
	global_load_dwordx2 v[214:215], v136, s[8:9] offset:32
	global_load_dwordx2 v[216:217], v137, s[8:9]
	global_load_dwordx2 v[218:219], v137, s[8:9] offset:32
	global_load_dwordx2 v[220:221], v138, s[8:9]
	global_load_dwordx2 v[222:223], v138, s[8:9] offset:32
	global_load_dwordx2 v[224:225], v139, s[8:9]
	global_load_dwordx2 v[226:227], v139, s[8:9] offset:32
	global_load_dwordx2 v[228:229], v136, s[8:9] offset:256
	global_load_dwordx2 v[230:231], v136, s[8:9] offset:288
	global_load_dwordx2 v[232:233], v137, s[8:9] offset:256
	global_load_dwordx2 v[234:235], v137, s[8:9] offset:288
	global_load_dwordx2 v[236:237], v138, s[8:9] offset:256
	global_load_dwordx2 v[238:239], v138, s[8:9] offset:288
	global_load_dwordx2 v[240:241], v139, s[8:9] offset:256
	global_load_dwordx2 v[242:243], v139, s[8:9] offset:288
	s_waitcnt vmcnt(30)
	v_lshlrev_b32_e32 v140, 16, v181
	v_and_b32_e32 v141, 0xffff0000, v181
	v_and_b32_e32 v181, 0xffff0000, v180
	v_lshlrev_b32_e32 v180, 16, v180
	v_lshlrev_b32_e32 v142, 16, v183
	v_and_b32_e32 v143, 0xffff0000, v183
	v_and_b32_e32 v183, 0xffff0000, v182
	v_lshlrev_b32_e32 v182, 16, v182
	v_pk_fma_f32 v[124:125], v[180:181], s[30:31], v[124:125] op_sel_hi:[1,0,1]
	v_pk_fma_f32 v[126:127], v[140:141], s[30:31], v[126:127] op_sel_hi:[1,0,1]
	v_pk_fma_f32 v[120:121], v[182:183], s[30:31], v[120:121] op_sel_hi:[1,0,1]
	v_pk_fma_f32 v[122:123], v[142:143], s[30:31], v[122:123] op_sel_hi:[1,0,1]
	v_cvt_pk_bf16_f32 v124, v124, v125
	v_cvt_pk_bf16_f32 v125, v126, v127
	v_cvt_pk_bf16_f32 v120, v120, v121
	v_cvt_pk_bf16_f32 v121, v122, v123
	global_store_dwordx2 v132, v[124:125], s[6:7]
	global_store_dwordx2 v132, v[120:121], s[6:7] offset:32
	s_waitcnt vmcnt(30)
	v_lshlrev_b32_e32 v140, 16, v185
	v_and_b32_e32 v141, 0xffff0000, v185
	v_and_b32_e32 v185, 0xffff0000, v184
	v_lshlrev_b32_e32 v184, 16, v184
	v_lshlrev_b32_e32 v142, 16, v187
	v_and_b32_e32 v143, 0xffff0000, v187
	v_and_b32_e32 v187, 0xffff0000, v186
	v_lshlrev_b32_e32 v186, 16, v186
	v_pk_fma_f32 v[112:113], v[184:185], s[30:31], v[112:113] op_sel_hi:[1,0,1]
	v_pk_fma_f32 v[114:115], v[140:141], s[30:31], v[114:115] op_sel_hi:[1,0,1]
	v_pk_fma_f32 v[116:117], v[186:187], s[30:31], v[116:117] op_sel_hi:[1,0,1]
	v_pk_fma_f32 v[118:119], v[142:143], s[30:31], v[118:119] op_sel_hi:[1,0,1]
	v_cvt_pk_bf16_f32 v112, v112, v113
	v_cvt_pk_bf16_f32 v113, v114, v115
	v_cvt_pk_bf16_f32 v116, v116, v117
	v_cvt_pk_bf16_f32 v117, v118, v119
	global_store_dwordx2 v133, v[112:113], s[6:7]
	global_store_dwordx2 v133, v[116:117], s[6:7] offset:32
	s_waitcnt vmcnt(30)
	v_lshlrev_b32_e32 v140, 16, v189
	v_and_b32_e32 v141, 0xffff0000, v189
	v_and_b32_e32 v189, 0xffff0000, v188
	v_lshlrev_b32_e32 v188, 16, v188
	v_lshlrev_b32_e32 v142, 16, v191
	v_and_b32_e32 v143, 0xffff0000, v191
	v_and_b32_e32 v191, 0xffff0000, v190
	v_lshlrev_b32_e32 v190, 16, v190
	v_pk_fma_f32 v[104:105], v[188:189], s[30:31], v[104:105] op_sel_hi:[1,0,1]
	v_pk_fma_f32 v[106:107], v[140:141], s[30:31], v[106:107] op_sel_hi:[1,0,1]
	v_pk_fma_f32 v[108:109], v[190:191], s[30:31], v[108:109] op_sel_hi:[1,0,1]
	v_pk_fma_f32 v[110:111], v[142:143], s[30:31], v[110:111] op_sel_hi:[1,0,1]
	v_cvt_pk_bf16_f32 v104, v104, v105
	v_cvt_pk_bf16_f32 v105, v106, v107
	v_cvt_pk_bf16_f32 v108, v108, v109
	v_cvt_pk_bf16_f32 v109, v110, v111
	global_store_dwordx2 v134, v[104:105], s[6:7]
	global_store_dwordx2 v134, v[108:109], s[6:7] offset:32
	s_waitcnt vmcnt(30)
	v_lshlrev_b32_e32 v140, 16, v193
	v_and_b32_e32 v141, 0xffff0000, v193
	v_and_b32_e32 v193, 0xffff0000, v192
	v_lshlrev_b32_e32 v192, 16, v192
	v_lshlrev_b32_e32 v142, 16, v195
	v_and_b32_e32 v143, 0xffff0000, v195
	v_and_b32_e32 v195, 0xffff0000, v194
	v_lshlrev_b32_e32 v194, 16, v194
	v_pk_fma_f32 v[96:97], v[192:193], s[30:31], v[96:97] op_sel_hi:[1,0,1]
	v_pk_fma_f32 v[98:99], v[140:141], s[30:31], v[98:99] op_sel_hi:[1,0,1]
	v_pk_fma_f32 v[100:101], v[194:195], s[30:31], v[100:101] op_sel_hi:[1,0,1]
	v_pk_fma_f32 v[102:103], v[142:143], s[30:31], v[102:103] op_sel_hi:[1,0,1]
	v_cvt_pk_bf16_f32 v96, v96, v97
	v_cvt_pk_bf16_f32 v97, v98, v99
	v_cvt_pk_bf16_f32 v100, v100, v101
	v_cvt_pk_bf16_f32 v101, v102, v103
	global_store_dwordx2 v135, v[96:97], s[6:7]
	global_store_dwordx2 v135, v[100:101], s[6:7] offset:32
	s_waitcnt vmcnt(30)
	v_lshlrev_b32_e32 v140, 16, v197
	v_and_b32_e32 v141, 0xffff0000, v197
	v_and_b32_e32 v197, 0xffff0000, v196
	v_lshlrev_b32_e32 v196, 16, v196
	v_lshlrev_b32_e32 v142, 16, v199
	v_and_b32_e32 v143, 0xffff0000, v199
	v_and_b32_e32 v199, 0xffff0000, v198
	v_lshlrev_b32_e32 v198, 16, v198
	v_pk_fma_f32 v[92:93], v[196:197], s[30:31], v[92:93] op_sel_hi:[1,0,1]
	v_pk_fma_f32 v[94:95], v[140:141], s[30:31], v[94:95] op_sel_hi:[1,0,1]
	v_pk_fma_f32 v[88:89], v[198:199], s[30:31], v[88:89] op_sel_hi:[1,0,1]
	v_pk_fma_f32 v[90:91], v[142:143], s[30:31], v[90:91] op_sel_hi:[1,0,1]
	v_cvt_pk_bf16_f32 v92, v92, v93
	v_cvt_pk_bf16_f32 v93, v94, v95
	v_cvt_pk_bf16_f32 v88, v88, v89
	v_cvt_pk_bf16_f32 v89, v90, v91
	global_store_dwordx2 v132, v[92:93], s[6:7] offset:256
	global_store_dwordx2 v132, v[88:89], s[6:7] offset:288
	s_waitcnt vmcnt(30)
	v_lshlrev_b32_e32 v140, 16, v201
	v_and_b32_e32 v141, 0xffff0000, v201
	v_and_b32_e32 v201, 0xffff0000, v200
	v_lshlrev_b32_e32 v200, 16, v200
	v_lshlrev_b32_e32 v142, 16, v203
	v_and_b32_e32 v143, 0xffff0000, v203
	v_and_b32_e32 v203, 0xffff0000, v202
	v_lshlrev_b32_e32 v202, 16, v202
	v_pk_fma_f32 v[80:81], v[200:201], s[30:31], v[80:81] op_sel_hi:[1,0,1]
	v_pk_fma_f32 v[82:83], v[140:141], s[30:31], v[82:83] op_sel_hi:[1,0,1]
	v_pk_fma_f32 v[84:85], v[202:203], s[30:31], v[84:85] op_sel_hi:[1,0,1]
	v_pk_fma_f32 v[86:87], v[142:143], s[30:31], v[86:87] op_sel_hi:[1,0,1]
	v_cvt_pk_bf16_f32 v80, v80, v81
	v_cvt_pk_bf16_f32 v81, v82, v83
	v_cvt_pk_bf16_f32 v84, v84, v85
	v_cvt_pk_bf16_f32 v85, v86, v87
	global_store_dwordx2 v133, v[80:81], s[6:7] offset:256
	global_store_dwordx2 v133, v[84:85], s[6:7] offset:288
	s_waitcnt vmcnt(30)
	v_lshlrev_b32_e32 v140, 16, v205
	v_and_b32_e32 v141, 0xffff0000, v205
	v_and_b32_e32 v205, 0xffff0000, v204
	v_lshlrev_b32_e32 v204, 16, v204
	v_lshlrev_b32_e32 v142, 16, v207
	v_and_b32_e32 v143, 0xffff0000, v207
	v_and_b32_e32 v207, 0xffff0000, v206
	v_lshlrev_b32_e32 v206, 16, v206
	v_pk_fma_f32 v[72:73], v[204:205], s[30:31], v[72:73] op_sel_hi:[1,0,1]
	v_pk_fma_f32 v[74:75], v[140:141], s[30:31], v[74:75] op_sel_hi:[1,0,1]
	v_pk_fma_f32 v[76:77], v[206:207], s[30:31], v[76:77] op_sel_hi:[1,0,1]
	v_pk_fma_f32 v[78:79], v[142:143], s[30:31], v[78:79] op_sel_hi:[1,0,1]
	v_cvt_pk_bf16_f32 v72, v72, v73
	v_cvt_pk_bf16_f32 v73, v74, v75
	v_cvt_pk_bf16_f32 v76, v76, v77
	v_cvt_pk_bf16_f32 v77, v78, v79
	global_store_dwordx2 v134, v[72:73], s[6:7] offset:256
	global_store_dwordx2 v134, v[76:77], s[6:7] offset:288
	s_waitcnt vmcnt(30)
	v_lshlrev_b32_e32 v140, 16, v209
	v_and_b32_e32 v141, 0xffff0000, v209
	v_and_b32_e32 v209, 0xffff0000, v208
	v_lshlrev_b32_e32 v208, 16, v208
	v_lshlrev_b32_e32 v142, 16, v211
	v_and_b32_e32 v143, 0xffff0000, v211
	v_and_b32_e32 v211, 0xffff0000, v210
	v_lshlrev_b32_e32 v210, 16, v210
	v_pk_fma_f32 v[64:65], v[208:209], s[30:31], v[64:65] op_sel_hi:[1,0,1]
	v_pk_fma_f32 v[66:67], v[140:141], s[30:31], v[66:67] op_sel_hi:[1,0,1]
	v_pk_fma_f32 v[68:69], v[210:211], s[30:31], v[68:69] op_sel_hi:[1,0,1]
	v_pk_fma_f32 v[70:71], v[142:143], s[30:31], v[70:71] op_sel_hi:[1,0,1]
	v_cvt_pk_bf16_f32 v64, v64, v65
	v_cvt_pk_bf16_f32 v65, v66, v67
	v_cvt_pk_bf16_f32 v68, v68, v69
	v_cvt_pk_bf16_f32 v69, v70, v71
	global_store_dwordx2 v135, v[64:65], s[6:7] offset:256
	global_store_dwordx2 v135, v[68:69], s[6:7] offset:288
	s_waitcnt vmcnt(30)
	v_lshlrev_b32_e32 v140, 16, v213
	v_and_b32_e32 v141, 0xffff0000, v213
	v_and_b32_e32 v213, 0xffff0000, v212
	v_lshlrev_b32_e32 v212, 16, v212
	v_lshlrev_b32_e32 v142, 16, v215
	v_and_b32_e32 v143, 0xffff0000, v215
	v_and_b32_e32 v215, 0xffff0000, v214
	v_lshlrev_b32_e32 v214, 16, v214
	v_pk_fma_f32 v[60:61], v[212:213], s[30:31], v[60:61] op_sel_hi:[1,0,1]
	v_pk_fma_f32 v[62:63], v[140:141], s[30:31], v[62:63] op_sel_hi:[1,0,1]
	v_pk_fma_f32 v[56:57], v[214:215], s[30:31], v[56:57] op_sel_hi:[1,0,1]
	v_pk_fma_f32 v[58:59], v[142:143], s[30:31], v[58:59] op_sel_hi:[1,0,1]
	v_cvt_pk_bf16_f32 v60, v60, v61
	v_cvt_pk_bf16_f32 v61, v62, v63
	v_cvt_pk_bf16_f32 v56, v56, v57
	v_cvt_pk_bf16_f32 v57, v58, v59
	global_store_dwordx2 v136, v[60:61], s[6:7]
	global_store_dwordx2 v136, v[56:57], s[6:7] offset:32
	s_waitcnt vmcnt(30)
	v_lshlrev_b32_e32 v140, 16, v217
	v_and_b32_e32 v141, 0xffff0000, v217
	v_and_b32_e32 v217, 0xffff0000, v216
	v_lshlrev_b32_e32 v216, 16, v216
	v_lshlrev_b32_e32 v142, 16, v219
	v_and_b32_e32 v143, 0xffff0000, v219
	v_and_b32_e32 v219, 0xffff0000, v218
	v_lshlrev_b32_e32 v218, 16, v218
	v_pk_fma_f32 v[48:49], v[216:217], s[30:31], v[48:49] op_sel_hi:[1,0,1]
	v_pk_fma_f32 v[50:51], v[140:141], s[30:31], v[50:51] op_sel_hi:[1,0,1]
	v_pk_fma_f32 v[52:53], v[218:219], s[30:31], v[52:53] op_sel_hi:[1,0,1]
	v_pk_fma_f32 v[54:55], v[142:143], s[30:31], v[54:55] op_sel_hi:[1,0,1]
	v_cvt_pk_bf16_f32 v48, v48, v49
	v_cvt_pk_bf16_f32 v49, v50, v51
	v_cvt_pk_bf16_f32 v52, v52, v53
	v_cvt_pk_bf16_f32 v53, v54, v55
	global_store_dwordx2 v137, v[48:49], s[6:7]
	global_store_dwordx2 v137, v[52:53], s[6:7] offset:32
	s_waitcnt vmcnt(30)
	v_lshlrev_b32_e32 v140, 16, v221
	v_and_b32_e32 v141, 0xffff0000, v221
	v_and_b32_e32 v221, 0xffff0000, v220
	v_lshlrev_b32_e32 v220, 16, v220
	v_lshlrev_b32_e32 v142, 16, v223
	v_and_b32_e32 v143, 0xffff0000, v223
	v_and_b32_e32 v223, 0xffff0000, v222
	v_lshlrev_b32_e32 v222, 16, v222
	v_pk_fma_f32 v[40:41], v[220:221], s[30:31], v[40:41] op_sel_hi:[1,0,1]
	v_pk_fma_f32 v[42:43], v[140:141], s[30:31], v[42:43] op_sel_hi:[1,0,1]
	v_pk_fma_f32 v[44:45], v[222:223], s[30:31], v[44:45] op_sel_hi:[1,0,1]
	v_pk_fma_f32 v[46:47], v[142:143], s[30:31], v[46:47] op_sel_hi:[1,0,1]
	v_cvt_pk_bf16_f32 v40, v40, v41
	v_cvt_pk_bf16_f32 v41, v42, v43
	v_cvt_pk_bf16_f32 v44, v44, v45
	v_cvt_pk_bf16_f32 v45, v46, v47
	global_store_dwordx2 v138, v[40:41], s[6:7]
	global_store_dwordx2 v138, v[44:45], s[6:7] offset:32
	s_waitcnt vmcnt(30)
	v_lshlrev_b32_e32 v140, 16, v225
	v_and_b32_e32 v141, 0xffff0000, v225
	v_and_b32_e32 v225, 0xffff0000, v224
	v_lshlrev_b32_e32 v224, 16, v224
	v_lshlrev_b32_e32 v142, 16, v227
	v_and_b32_e32 v143, 0xffff0000, v227
	v_and_b32_e32 v227, 0xffff0000, v226
	v_lshlrev_b32_e32 v226, 16, v226
	v_pk_fma_f32 v[32:33], v[224:225], s[30:31], v[32:33] op_sel_hi:[1,0,1]
	v_pk_fma_f32 v[34:35], v[140:141], s[30:31], v[34:35] op_sel_hi:[1,0,1]
	v_pk_fma_f32 v[36:37], v[226:227], s[30:31], v[36:37] op_sel_hi:[1,0,1]
	v_pk_fma_f32 v[38:39], v[142:143], s[30:31], v[38:39] op_sel_hi:[1,0,1]
	v_cvt_pk_bf16_f32 v32, v32, v33
	v_cvt_pk_bf16_f32 v33, v34, v35
	v_cvt_pk_bf16_f32 v36, v36, v37
	v_cvt_pk_bf16_f32 v37, v38, v39
	global_store_dwordx2 v139, v[32:33], s[6:7]
	global_store_dwordx2 v139, v[36:37], s[6:7] offset:32
	s_waitcnt vmcnt(30)
	v_lshlrev_b32_e32 v140, 16, v229
	v_and_b32_e32 v141, 0xffff0000, v229
	v_and_b32_e32 v229, 0xffff0000, v228
	v_lshlrev_b32_e32 v228, 16, v228
	v_lshlrev_b32_e32 v142, 16, v231
	v_and_b32_e32 v143, 0xffff0000, v231
	v_and_b32_e32 v231, 0xffff0000, v230
	v_lshlrev_b32_e32 v230, 16, v230
	v_pk_fma_f32 v[28:29], v[228:229], s[30:31], v[28:29] op_sel_hi:[1,0,1]
	v_pk_fma_f32 v[30:31], v[140:141], s[30:31], v[30:31] op_sel_hi:[1,0,1]
	v_pk_fma_f32 v[24:25], v[230:231], s[30:31], v[24:25] op_sel_hi:[1,0,1]
	v_pk_fma_f32 v[26:27], v[142:143], s[30:31], v[26:27] op_sel_hi:[1,0,1]
	v_cvt_pk_bf16_f32 v28, v28, v29
	v_cvt_pk_bf16_f32 v29, v30, v31
	v_cvt_pk_bf16_f32 v24, v24, v25
	v_cvt_pk_bf16_f32 v25, v26, v27
	global_store_dwordx2 v136, v[28:29], s[6:7] offset:256
	global_store_dwordx2 v136, v[24:25], s[6:7] offset:288
	s_waitcnt vmcnt(30)
	v_lshlrev_b32_e32 v140, 16, v233
	v_and_b32_e32 v141, 0xffff0000, v233
	v_and_b32_e32 v233, 0xffff0000, v232
	v_lshlrev_b32_e32 v232, 16, v232
	v_lshlrev_b32_e32 v142, 16, v235
	v_and_b32_e32 v143, 0xffff0000, v235
	v_and_b32_e32 v235, 0xffff0000, v234
	v_lshlrev_b32_e32 v234, 16, v234
	v_pk_fma_f32 v[16:17], v[232:233], s[30:31], v[16:17] op_sel_hi:[1,0,1]
	v_pk_fma_f32 v[18:19], v[140:141], s[30:31], v[18:19] op_sel_hi:[1,0,1]
	v_pk_fma_f32 v[20:21], v[234:235], s[30:31], v[20:21] op_sel_hi:[1,0,1]
	v_pk_fma_f32 v[22:23], v[142:143], s[30:31], v[22:23] op_sel_hi:[1,0,1]
	v_cvt_pk_bf16_f32 v16, v16, v17
	v_cvt_pk_bf16_f32 v17, v18, v19
	v_cvt_pk_bf16_f32 v20, v20, v21
	v_cvt_pk_bf16_f32 v21, v22, v23
	global_store_dwordx2 v137, v[16:17], s[6:7] offset:256
	global_store_dwordx2 v137, v[20:21], s[6:7] offset:288
	s_waitcnt vmcnt(30)
	v_lshlrev_b32_e32 v140, 16, v237
	v_and_b32_e32 v141, 0xffff0000, v237
	v_and_b32_e32 v237, 0xffff0000, v236
	v_lshlrev_b32_e32 v236, 16, v236
	v_lshlrev_b32_e32 v142, 16, v239
	v_and_b32_e32 v143, 0xffff0000, v239
	v_and_b32_e32 v239, 0xffff0000, v238
	v_lshlrev_b32_e32 v238, 16, v238
	v_pk_fma_f32 v[8:9], v[236:237], s[30:31], v[8:9] op_sel_hi:[1,0,1]
	v_pk_fma_f32 v[10:11], v[140:141], s[30:31], v[10:11] op_sel_hi:[1,0,1]
	v_pk_fma_f32 v[12:13], v[238:239], s[30:31], v[12:13] op_sel_hi:[1,0,1]
	v_pk_fma_f32 v[14:15], v[142:143], s[30:31], v[14:15] op_sel_hi:[1,0,1]
	v_cvt_pk_bf16_f32 v8, v8, v9
	v_cvt_pk_bf16_f32 v9, v10, v11
	v_cvt_pk_bf16_f32 v12, v12, v13
	v_cvt_pk_bf16_f32 v13, v14, v15
	global_store_dwordx2 v138, v[8:9], s[6:7] offset:256
	global_store_dwordx2 v138, v[12:13], s[6:7] offset:288
	s_waitcnt vmcnt(30)
	v_lshlrev_b32_e32 v140, 16, v241
	v_and_b32_e32 v141, 0xffff0000, v241
	v_and_b32_e32 v241, 0xffff0000, v240
	v_lshlrev_b32_e32 v240, 16, v240
	v_lshlrev_b32_e32 v142, 16, v243
	v_and_b32_e32 v143, 0xffff0000, v243
	v_and_b32_e32 v243, 0xffff0000, v242
	v_lshlrev_b32_e32 v242, 16, v242
	v_pk_fma_f32 v[0:1], v[240:241], s[30:31], v[0:1] op_sel_hi:[1,0,1]
	v_pk_fma_f32 v[2:3], v[140:141], s[30:31], v[2:3] op_sel_hi:[1,0,1]
	v_pk_fma_f32 v[4:5], v[242:243], s[30:31], v[4:5] op_sel_hi:[1,0,1]
	v_pk_fma_f32 v[6:7], v[142:143], s[30:31], v[6:7] op_sel_hi:[1,0,1]
	v_cvt_pk_bf16_f32 v0, v0, v1
	v_cvt_pk_bf16_f32 v1, v2, v3
	v_cvt_pk_bf16_f32 v4, v4, v5
	v_cvt_pk_bf16_f32 v5, v6, v7
	global_store_dwordx2 v139, v[0:1], s[6:7] offset:256
	global_store_dwordx2 v139, v[4:5], s[6:7] offset:288
	s_andn2_b64 vcc, exec, s[0:1]
	s_mov_b32 s40, s56
	s_mov_b32 s42, s57
	s_cbranch_vccz .LBB0_758

.LBB0_1682:
	s_or_b64 exec, exec, s[44:45]
	s_lshl_b32 s98, s40, 1
	s_lshl_b32 s99, s42, 11
	s_add_i32 s98, s98, s99
	v_lshlrev_b32_e32 v132, 6, v152
	v_lshl_add_u32 v132, v153, 3, v132
	v_lshl_add_u32 v132, v155, 11, v132
	v_lshl_add_u32 v132, v145, 17, v132
	v_add_u32_e32 v132, s98, v132
	v_add_u32_e32 v133, 0x8000, v132
	v_add_u32_e32 v134, 0x10000, v132
	v_add_u32_e32 v135, 0x18000, v132
	v_add_u32_e32 v136, 0x40000, v132
	v_add_u32_e32 v137, 0x48000, v132
	v_add_u32_e32 v138, 0x50000, v132
	v_add_u32_e32 v139, 0x58000, v132
	global_load_dwordx2 v[178:179], v132, s[6:7]
	global_load_dwordx2 v[180:181], v132, s[6:7] offset:32
	global_load_dwordx2 v[182:183], v133, s[6:7]
	global_load_dwordx2 v[184:185], v133, s[6:7] offset:32
	global_load_dwordx2 v[186:187], v134, s[6:7]
	global_load_dwordx2 v[188:189], v134, s[6:7] offset:32
	global_load_dwordx2 v[190:191], v135, s[6:7]
	global_load_dwordx2 v[192:193], v135, s[6:7] offset:32
	global_load_dwordx2 v[194:195], v132, s[6:7] offset:256
	global_load_dwordx2 v[196:197], v132, s[6:7] offset:288
	global_load_dwordx2 v[198:199], v133, s[6:7] offset:256
	global_load_dwordx2 v[200:201], v133, s[6:7] offset:288
	global_load_dwordx2 v[202:203], v134, s[6:7] offset:256
	global_load_dwordx2 v[204:205], v134, s[6:7] offset:288
	global_load_dwordx2 v[206:207], v135, s[6:7] offset:256
	global_load_dwordx2 v[208:209], v135, s[6:7] offset:288
	global_load_dwordx2 v[210:211], v136, s[6:7]
	global_load_dwordx2 v[212:213], v136, s[6:7] offset:32
	global_load_dwordx2 v[214:215], v137, s[6:7]
	global_load_dwordx2 v[216:217], v137, s[6:7] offset:32
	global_load_dwordx2 v[218:219], v138, s[6:7]
	global_load_dwordx2 v[220:221], v138, s[6:7] offset:32
	global_load_dwordx2 v[222:223], v139, s[6:7]
	global_load_dwordx2 v[224:225], v139, s[6:7] offset:32
	global_load_dwordx2 v[226:227], v136, s[6:7] offset:256
	global_load_dwordx2 v[228:229], v136, s[6:7] offset:288
	global_load_dwordx2 v[230:231], v137, s[6:7] offset:256
	global_load_dwordx2 v[232:233], v137, s[6:7] offset:288
	global_load_dwordx2 v[234:235], v138, s[6:7] offset:256
	global_load_dwordx2 v[236:237], v138, s[6:7] offset:288
	global_load_dwordx2 v[238:239], v139, s[6:7] offset:256
	global_load_dwordx2 v[240:241], v139, s[6:7] offset:288
	s_waitcnt vmcnt(30)
	v_lshlrev_b32_e32 v140, 16, v179
	v_and_b32_e32 v141, 0xffff0000, v179
	v_and_b32_e32 v179, 0xffff0000, v178
	v_lshlrev_b32_e32 v178, 16, v178
	v_lshlrev_b32_e32 v142, 16, v181
	v_and_b32_e32 v143, 0xffff0000, v181
	v_and_b32_e32 v181, 0xffff0000, v180
	v_lshlrev_b32_e32 v180, 16, v180
	v_pk_fma_f32 v[124:125], v[178:179], s[38:39], v[124:125] op_sel_hi:[1,0,1]
	v_pk_fma_f32 v[126:127], v[140:141], s[38:39], v[126:127] op_sel_hi:[1,0,1]
	v_pk_fma_f32 v[120:121], v[180:181], s[38:39], v[120:121] op_sel_hi:[1,0,1]
	v_pk_fma_f32 v[122:123], v[142:143], s[38:39], v[122:123] op_sel_hi:[1,0,1]
	v_cvt_pk_bf16_f32 v124, v124, v125
	v_cvt_pk_bf16_f32 v125, v126, v127
	v_cvt_pk_bf16_f32 v120, v120, v121
	v_cvt_pk_bf16_f32 v121, v122, v123
	global_store_dwordx2 v132, v[124:125], s[8:9]
	global_store_dwordx2 v132, v[120:121], s[8:9] offset:32
	s_waitcnt vmcnt(30)
	v_lshlrev_b32_e32 v140, 16, v183
	v_and_b32_e32 v141, 0xffff0000, v183
	v_and_b32_e32 v183, 0xffff0000, v182
	v_lshlrev_b32_e32 v182, 16, v182
	v_lshlrev_b32_e32 v142, 16, v185
	v_and_b32_e32 v143, 0xffff0000, v185
	v_and_b32_e32 v185, 0xffff0000, v184
	v_lshlrev_b32_e32 v184, 16, v184
	v_pk_fma_f32 v[112:113], v[182:183], s[38:39], v[112:113] op_sel_hi:[1,0,1]
	v_pk_fma_f32 v[114:115], v[140:141], s[38:39], v[114:115] op_sel_hi:[1,0,1]
	v_pk_fma_f32 v[116:117], v[184:185], s[38:39], v[116:117] op_sel_hi:[1,0,1]
	v_pk_fma_f32 v[118:119], v[142:143], s[38:39], v[118:119] op_sel_hi:[1,0,1]
	v_cvt_pk_bf16_f32 v112, v112, v113
	v_cvt_pk_bf16_f32 v113, v114, v115
	v_cvt_pk_bf16_f32 v116, v116, v117
	v_cvt_pk_bf16_f32 v117, v118, v119
	global_store_dwordx2 v133, v[112:113], s[8:9]
	global_store_dwordx2 v133, v[116:117], s[8:9] offset:32
	s_waitcnt vmcnt(30)
	v_lshlrev_b32_e32 v140, 16, v187
	v_and_b32_e32 v141, 0xffff0000, v187
	v_and_b32_e32 v187, 0xffff0000, v186
	v_lshlrev_b32_e32 v186, 16, v186
	v_lshlrev_b32_e32 v142, 16, v189
	v_and_b32_e32 v143, 0xffff0000, v189
	v_and_b32_e32 v189, 0xffff0000, v188
	v_lshlrev_b32_e32 v188, 16, v188
	v_pk_fma_f32 v[104:105], v[186:187], s[38:39], v[104:105] op_sel_hi:[1,0,1]
	v_pk_fma_f32 v[106:107], v[140:141], s[38:39], v[106:107] op_sel_hi:[1,0,1]
	v_pk_fma_f32 v[108:109], v[188:189], s[38:39], v[108:109] op_sel_hi:[1,0,1]
	v_pk_fma_f32 v[110:111], v[142:143], s[38:39], v[110:111] op_sel_hi:[1,0,1]
	v_cvt_pk_bf16_f32 v104, v104, v105
	v_cvt_pk_bf16_f32 v105, v106, v107
	v_cvt_pk_bf16_f32 v108, v108, v109
	v_cvt_pk_bf16_f32 v109, v110, v111
	global_store_dwordx2 v134, v[104:105], s[8:9]
	global_store_dwordx2 v134, v[108:109], s[8:9] offset:32
	s_waitcnt vmcnt(30)
	v_lshlrev_b32_e32 v140, 16, v191
	v_and_b32_e32 v141, 0xffff0000, v191
	v_and_b32_e32 v191, 0xffff0000, v190
	v_lshlrev_b32_e32 v190, 16, v190
	v_lshlrev_b32_e32 v142, 16, v193
	v_and_b32_e32 v143, 0xffff0000, v193
	v_and_b32_e32 v193, 0xffff0000, v192
	v_lshlrev_b32_e32 v192, 16, v192
	v_pk_fma_f32 v[96:97], v[190:191], s[38:39], v[96:97] op_sel_hi:[1,0,1]
	v_pk_fma_f32 v[98:99], v[140:141], s[38:39], v[98:99] op_sel_hi:[1,0,1]
	v_pk_fma_f32 v[100:101], v[192:193], s[38:39], v[100:101] op_sel_hi:[1,0,1]
	v_pk_fma_f32 v[102:103], v[142:143], s[38:39], v[102:103] op_sel_hi:[1,0,1]
	v_cvt_pk_bf16_f32 v96, v96, v97
	v_cvt_pk_bf16_f32 v97, v98, v99
	v_cvt_pk_bf16_f32 v100, v100, v101
	v_cvt_pk_bf16_f32 v101, v102, v103
	global_store_dwordx2 v135, v[96:97], s[8:9]
	global_store_dwordx2 v135, v[100:101], s[8:9] offset:32
	s_waitcnt vmcnt(30)
	v_lshlrev_b32_e32 v140, 16, v195
	v_and_b32_e32 v141, 0xffff0000, v195
	v_and_b32_e32 v195, 0xffff0000, v194
	v_lshlrev_b32_e32 v194, 16, v194
	v_lshlrev_b32_e32 v142, 16, v197
	v_and_b32_e32 v143, 0xffff0000, v197
	v_and_b32_e32 v197, 0xffff0000, v196
	v_lshlrev_b32_e32 v196, 16, v196
	v_pk_fma_f32 v[92:93], v[194:195], s[38:39], v[92:93] op_sel_hi:[1,0,1]
	v_pk_fma_f32 v[94:95], v[140:141], s[38:39], v[94:95] op_sel_hi:[1,0,1]
	v_pk_fma_f32 v[88:89], v[196:197], s[38:39], v[88:89] op_sel_hi:[1,0,1]
	v_pk_fma_f32 v[90:91], v[142:143], s[38:39], v[90:91] op_sel_hi:[1,0,1]
	v_cvt_pk_bf16_f32 v92, v92, v93
	v_cvt_pk_bf16_f32 v93, v94, v95
	v_cvt_pk_bf16_f32 v88, v88, v89
	v_cvt_pk_bf16_f32 v89, v90, v91
	global_store_dwordx2 v132, v[92:93], s[8:9] offset:256
	global_store_dwordx2 v132, v[88:89], s[8:9] offset:288
	s_waitcnt vmcnt(30)
	v_lshlrev_b32_e32 v140, 16, v199
	v_and_b32_e32 v141, 0xffff0000, v199
	v_and_b32_e32 v199, 0xffff0000, v198
	v_lshlrev_b32_e32 v198, 16, v198
	v_lshlrev_b32_e32 v142, 16, v201
	v_and_b32_e32 v143, 0xffff0000, v201
	v_and_b32_e32 v201, 0xffff0000, v200
	v_lshlrev_b32_e32 v200, 16, v200
	v_pk_fma_f32 v[80:81], v[198:199], s[38:39], v[80:81] op_sel_hi:[1,0,1]
	v_pk_fma_f32 v[82:83], v[140:141], s[38:39], v[82:83] op_sel_hi:[1,0,1]
	v_pk_fma_f32 v[84:85], v[200:201], s[38:39], v[84:85] op_sel_hi:[1,0,1]
	v_pk_fma_f32 v[86:87], v[142:143], s[38:39], v[86:87] op_sel_hi:[1,0,1]
	v_cvt_pk_bf16_f32 v80, v80, v81
	v_cvt_pk_bf16_f32 v81, v82, v83
	v_cvt_pk_bf16_f32 v84, v84, v85
	v_cvt_pk_bf16_f32 v85, v86, v87
	global_store_dwordx2 v133, v[80:81], s[8:9] offset:256
	global_store_dwordx2 v133, v[84:85], s[8:9] offset:288
	s_waitcnt vmcnt(30)
	v_lshlrev_b32_e32 v140, 16, v203
	v_and_b32_e32 v141, 0xffff0000, v203
	v_and_b32_e32 v203, 0xffff0000, v202
	v_lshlrev_b32_e32 v202, 16, v202
	v_lshlrev_b32_e32 v142, 16, v205
	v_and_b32_e32 v143, 0xffff0000, v205
	v_and_b32_e32 v205, 0xffff0000, v204
	v_lshlrev_b32_e32 v204, 16, v204
	v_pk_fma_f32 v[72:73], v[202:203], s[38:39], v[72:73] op_sel_hi:[1,0,1]
	v_pk_fma_f32 v[74:75], v[140:141], s[38:39], v[74:75] op_sel_hi:[1,0,1]
	v_pk_fma_f32 v[76:77], v[204:205], s[38:39], v[76:77] op_sel_hi:[1,0,1]
	v_pk_fma_f32 v[78:79], v[142:143], s[38:39], v[78:79] op_sel_hi:[1,0,1]
	v_cvt_pk_bf16_f32 v72, v72, v73
	v_cvt_pk_bf16_f32 v73, v74, v75
	v_cvt_pk_bf16_f32 v76, v76, v77
	v_cvt_pk_bf16_f32 v77, v78, v79
	global_store_dwordx2 v134, v[72:73], s[8:9] offset:256
	global_store_dwordx2 v134, v[76:77], s[8:9] offset:288
	s_waitcnt vmcnt(30)
	v_lshlrev_b32_e32 v140, 16, v207
	v_and_b32_e32 v141, 0xffff0000, v207
	v_and_b32_e32 v207, 0xffff0000, v206
	v_lshlrev_b32_e32 v206, 16, v206
	v_lshlrev_b32_e32 v142, 16, v209
	v_and_b32_e32 v143, 0xffff0000, v209
	v_and_b32_e32 v209, 0xffff0000, v208
	v_lshlrev_b32_e32 v208, 16, v208
	v_pk_fma_f32 v[64:65], v[206:207], s[38:39], v[64:65] op_sel_hi:[1,0,1]
	v_pk_fma_f32 v[66:67], v[140:141], s[38:39], v[66:67] op_sel_hi:[1,0,1]
	v_pk_fma_f32 v[68:69], v[208:209], s[38:39], v[68:69] op_sel_hi:[1,0,1]
	v_pk_fma_f32 v[70:71], v[142:143], s[38:39], v[70:71] op_sel_hi:[1,0,1]
	v_cvt_pk_bf16_f32 v64, v64, v65
	v_cvt_pk_bf16_f32 v65, v66, v67
	v_cvt_pk_bf16_f32 v68, v68, v69
	v_cvt_pk_bf16_f32 v69, v70, v71
	global_store_dwordx2 v135, v[64:65], s[8:9] offset:256
	global_store_dwordx2 v135, v[68:69], s[8:9] offset:288
	s_waitcnt vmcnt(30)
	v_lshlrev_b32_e32 v140, 16, v211
	v_and_b32_e32 v141, 0xffff0000, v211
	v_and_b32_e32 v211, 0xffff0000, v210
	v_lshlrev_b32_e32 v210, 16, v210
	v_lshlrev_b32_e32 v142, 16, v213
	v_and_b32_e32 v143, 0xffff0000, v213
	v_and_b32_e32 v213, 0xffff0000, v212
	v_lshlrev_b32_e32 v212, 16, v212
	v_pk_fma_f32 v[60:61], v[210:211], s[38:39], v[60:61] op_sel_hi:[1,0,1]
	v_pk_fma_f32 v[62:63], v[140:141], s[38:39], v[62:63] op_sel_hi:[1,0,1]
	v_pk_fma_f32 v[56:57], v[212:213], s[38:39], v[56:57] op_sel_hi:[1,0,1]
	v_pk_fma_f32 v[58:59], v[142:143], s[38:39], v[58:59] op_sel_hi:[1,0,1]
	v_cvt_pk_bf16_f32 v60, v60, v61
	v_cvt_pk_bf16_f32 v61, v62, v63
	v_cvt_pk_bf16_f32 v56, v56, v57
	v_cvt_pk_bf16_f32 v57, v58, v59
	global_store_dwordx2 v136, v[60:61], s[8:9]
	global_store_dwordx2 v136, v[56:57], s[8:9] offset:32
	s_waitcnt vmcnt(30)
	v_lshlrev_b32_e32 v140, 16, v215
	v_and_b32_e32 v141, 0xffff0000, v215
	v_and_b32_e32 v215, 0xffff0000, v214
	v_lshlrev_b32_e32 v214, 16, v214
	v_lshlrev_b32_e32 v142, 16, v217
	v_and_b32_e32 v143, 0xffff0000, v217
	v_and_b32_e32 v217, 0xffff0000, v216
	v_lshlrev_b32_e32 v216, 16, v216
	v_pk_fma_f32 v[48:49], v[214:215], s[38:39], v[48:49] op_sel_hi:[1,0,1]
	v_pk_fma_f32 v[50:51], v[140:141], s[38:39], v[50:51] op_sel_hi:[1,0,1]
	v_pk_fma_f32 v[52:53], v[216:217], s[38:39], v[52:53] op_sel_hi:[1,0,1]
	v_pk_fma_f32 v[54:55], v[142:143], s[38:39], v[54:55] op_sel_hi:[1,0,1]
	v_cvt_pk_bf16_f32 v48, v48, v49
	v_cvt_pk_bf16_f32 v49, v50, v51
	v_cvt_pk_bf16_f32 v52, v52, v53
	v_cvt_pk_bf16_f32 v53, v54, v55
	global_store_dwordx2 v137, v[48:49], s[8:9]
	global_store_dwordx2 v137, v[52:53], s[8:9] offset:32
	s_waitcnt vmcnt(30)
	v_lshlrev_b32_e32 v140, 16, v219
	v_and_b32_e32 v141, 0xffff0000, v219
	v_and_b32_e32 v219, 0xffff0000, v218
	v_lshlrev_b32_e32 v218, 16, v218
	v_lshlrev_b32_e32 v142, 16, v221
	v_and_b32_e32 v143, 0xffff0000, v221
	v_and_b32_e32 v221, 0xffff0000, v220
	v_lshlrev_b32_e32 v220, 16, v220
	v_pk_fma_f32 v[40:41], v[218:219], s[38:39], v[40:41] op_sel_hi:[1,0,1]
	v_pk_fma_f32 v[42:43], v[140:141], s[38:39], v[42:43] op_sel_hi:[1,0,1]
	v_pk_fma_f32 v[44:45], v[220:221], s[38:39], v[44:45] op_sel_hi:[1,0,1]
	v_pk_fma_f32 v[46:47], v[142:143], s[38:39], v[46:47] op_sel_hi:[1,0,1]
	v_cvt_pk_bf16_f32 v40, v40, v41
	v_cvt_pk_bf16_f32 v41, v42, v43
	v_cvt_pk_bf16_f32 v44, v44, v45
	v_cvt_pk_bf16_f32 v45, v46, v47
	global_store_dwordx2 v138, v[40:41], s[8:9]
	global_store_dwordx2 v138, v[44:45], s[8:9] offset:32
	s_waitcnt vmcnt(30)
	v_lshlrev_b32_e32 v140, 16, v223
	v_and_b32_e32 v141, 0xffff0000, v223
	v_and_b32_e32 v223, 0xffff0000, v222
	v_lshlrev_b32_e32 v222, 16, v222
	v_lshlrev_b32_e32 v142, 16, v225
	v_and_b32_e32 v143, 0xffff0000, v225
	v_and_b32_e32 v225, 0xffff0000, v224
	v_lshlrev_b32_e32 v224, 16, v224
	v_pk_fma_f32 v[32:33], v[222:223], s[38:39], v[32:33] op_sel_hi:[1,0,1]
	v_pk_fma_f32 v[34:35], v[140:141], s[38:39], v[34:35] op_sel_hi:[1,0,1]
	v_pk_fma_f32 v[36:37], v[224:225], s[38:39], v[36:37] op_sel_hi:[1,0,1]
	v_pk_fma_f32 v[38:39], v[142:143], s[38:39], v[38:39] op_sel_hi:[1,0,1]
	v_cvt_pk_bf16_f32 v32, v32, v33
	v_cvt_pk_bf16_f32 v33, v34, v35
	v_cvt_pk_bf16_f32 v36, v36, v37
	v_cvt_pk_bf16_f32 v37, v38, v39
	global_store_dwordx2 v139, v[32:33], s[8:9]
	global_store_dwordx2 v139, v[36:37], s[8:9] offset:32
	s_waitcnt vmcnt(30)
	v_lshlrev_b32_e32 v140, 16, v227
	v_and_b32_e32 v141, 0xffff0000, v227
	v_and_b32_e32 v227, 0xffff0000, v226
	v_lshlrev_b32_e32 v226, 16, v226
	v_lshlrev_b32_e32 v142, 16, v229
	v_and_b32_e32 v143, 0xffff0000, v229
	v_and_b32_e32 v229, 0xffff0000, v228
	v_lshlrev_b32_e32 v228, 16, v228
	v_pk_fma_f32 v[28:29], v[226:227], s[38:39], v[28:29] op_sel_hi:[1,0,1]
	v_pk_fma_f32 v[30:31], v[140:141], s[38:39], v[30:31] op_sel_hi:[1,0,1]
	v_pk_fma_f32 v[24:25], v[228:229], s[38:39], v[24:25] op_sel_hi:[1,0,1]
	v_pk_fma_f32 v[26:27], v[142:143], s[38:39], v[26:27] op_sel_hi:[1,0,1]
	v_cvt_pk_bf16_f32 v28, v28, v29
	v_cvt_pk_bf16_f32 v29, v30, v31
	v_cvt_pk_bf16_f32 v24, v24, v25
	v_cvt_pk_bf16_f32 v25, v26, v27
	global_store_dwordx2 v136, v[28:29], s[8:9] offset:256
	global_store_dwordx2 v136, v[24:25], s[8:9] offset:288
	s_waitcnt vmcnt(30)
	v_lshlrev_b32_e32 v140, 16, v231
	v_and_b32_e32 v141, 0xffff0000, v231
	v_and_b32_e32 v231, 0xffff0000, v230
	v_lshlrev_b32_e32 v230, 16, v230
	v_lshlrev_b32_e32 v142, 16, v233
	v_and_b32_e32 v143, 0xffff0000, v233
	v_and_b32_e32 v233, 0xffff0000, v232
	v_lshlrev_b32_e32 v232, 16, v232
	v_pk_fma_f32 v[16:17], v[230:231], s[38:39], v[16:17] op_sel_hi:[1,0,1]
	v_pk_fma_f32 v[18:19], v[140:141], s[38:39], v[18:19] op_sel_hi:[1,0,1]
	v_pk_fma_f32 v[20:21], v[232:233], s[38:39], v[20:21] op_sel_hi:[1,0,1]
	v_pk_fma_f32 v[22:23], v[142:143], s[38:39], v[22:23] op_sel_hi:[1,0,1]
	v_cvt_pk_bf16_f32 v16, v16, v17
	v_cvt_pk_bf16_f32 v17, v18, v19
	v_cvt_pk_bf16_f32 v20, v20, v21
	v_cvt_pk_bf16_f32 v21, v22, v23
	global_store_dwordx2 v137, v[16:17], s[8:9] offset:256
	global_store_dwordx2 v137, v[20:21], s[8:9] offset:288
	s_waitcnt vmcnt(30)
	v_lshlrev_b32_e32 v140, 16, v235
	v_and_b32_e32 v141, 0xffff0000, v235
	v_and_b32_e32 v235, 0xffff0000, v234
	v_lshlrev_b32_e32 v234, 16, v234
	v_lshlrev_b32_e32 v142, 16, v237
	v_and_b32_e32 v143, 0xffff0000, v237
	v_and_b32_e32 v237, 0xffff0000, v236
	v_lshlrev_b32_e32 v236, 16, v236
	v_pk_fma_f32 v[8:9], v[234:235], s[38:39], v[8:9] op_sel_hi:[1,0,1]
	v_pk_fma_f32 v[10:11], v[140:141], s[38:39], v[10:11] op_sel_hi:[1,0,1]
	v_pk_fma_f32 v[12:13], v[236:237], s[38:39], v[12:13] op_sel_hi:[1,0,1]
	v_pk_fma_f32 v[14:15], v[142:143], s[38:39], v[14:15] op_sel_hi:[1,0,1]
	v_cvt_pk_bf16_f32 v8, v8, v9
	v_cvt_pk_bf16_f32 v9, v10, v11
	v_cvt_pk_bf16_f32 v12, v12, v13
	v_cvt_pk_bf16_f32 v13, v14, v15
	global_store_dwordx2 v138, v[8:9], s[8:9] offset:256
	global_store_dwordx2 v138, v[12:13], s[8:9] offset:288
	s_waitcnt vmcnt(30)
	v_lshlrev_b32_e32 v140, 16, v239
	v_and_b32_e32 v141, 0xffff0000, v239
	v_and_b32_e32 v239, 0xffff0000, v238
	v_lshlrev_b32_e32 v238, 16, v238
	v_lshlrev_b32_e32 v142, 16, v241
	v_and_b32_e32 v143, 0xffff0000, v241
	v_and_b32_e32 v241, 0xffff0000, v240
	v_lshlrev_b32_e32 v240, 16, v240
	v_pk_fma_f32 v[0:1], v[238:239], s[38:39], v[0:1] op_sel_hi:[1,0,1]
	v_pk_fma_f32 v[2:3], v[140:141], s[38:39], v[2:3] op_sel_hi:[1,0,1]
	v_pk_fma_f32 v[4:5], v[240:241], s[38:39], v[4:5] op_sel_hi:[1,0,1]
	v_pk_fma_f32 v[6:7], v[142:143], s[38:39], v[6:7] op_sel_hi:[1,0,1]
	v_cvt_pk_bf16_f32 v0, v0, v1
	v_cvt_pk_bf16_f32 v1, v2, v3
	v_cvt_pk_bf16_f32 v4, v4, v5
	v_cvt_pk_bf16_f32 v5, v6, v7
	global_store_dwordx2 v139, v[0:1], s[8:9] offset:256
	global_store_dwordx2 v139, v[4:5], s[8:9] offset:288
	s_andn2_b64 vcc, exec, s[0:1]
	s_mov_b32 s43, s61
	s_mov_b32 s42, s62
	s_cbranch_vccz .LBB0_1691

.LBB0_1863:
	s_or_b64 exec, exec, s[38:39]
	s_lshl_b32 s98, s60, 1
	s_lshl_b32 s99, s61, 11
	s_add_i32 s98, s98, s99
	v_lshlrev_b32_e32 v132, 6, v155
	v_lshl_add_u32 v132, v156, 3, v132
	v_lshl_add_u32 v132, v157, 11, v132
	v_lshl_add_u32 v132, v153, 17, v132
	v_add_u32_e32 v132, s98, v132
	v_add_u32_e32 v133, 0x8000, v132
	v_add_u32_e32 v134, 0x10000, v132
	v_add_u32_e32 v135, 0x18000, v132
	v_add_u32_e32 v136, 0x40000, v132
	v_add_u32_e32 v137, 0x48000, v132
	v_add_u32_e32 v138, 0x50000, v132
	v_add_u32_e32 v139, 0x58000, v132
	global_load_dwordx2 v[180:181], v132, s[8:9]
	global_load_dwordx2 v[182:183], v132, s[8:9] offset:32
	global_load_dwordx2 v[184:185], v133, s[8:9]
	global_load_dwordx2 v[186:187], v133, s[8:9] offset:32
	global_load_dwordx2 v[188:189], v134, s[8:9]
	global_load_dwordx2 v[190:191], v134, s[8:9] offset:32
	global_load_dwordx2 v[192:193], v135, s[8:9]
	global_load_dwordx2 v[194:195], v135, s[8:9] offset:32
	global_load_dwordx2 v[196:197], v132, s[8:9] offset:256
	global_load_dwordx2 v[198:199], v132, s[8:9] offset:288
	global_load_dwordx2 v[200:201], v133, s[8:9] offset:256
	global_load_dwordx2 v[202:203], v133, s[8:9] offset:288
	global_load_dwordx2 v[204:205], v134, s[8:9] offset:256
	global_load_dwordx2 v[206:207], v134, s[8:9] offset:288
	global_load_dwordx2 v[208:209], v135, s[8:9] offset:256
	global_load_dwordx2 v[210:211], v135, s[8:9] offset:288
	global_load_dwordx2 v[212:213], v136, s[8:9]
	global_load_dwordx2 v[214:215], v136, s[8:9] offset:32
	global_load_dwordx2 v[216:217], v137, s[8:9]
	global_load_dwordx2 v[218:219], v137, s[8:9] offset:32
	global_load_dwordx2 v[220:221], v138, s[8:9]
	global_load_dwordx2 v[222:223], v138, s[8:9] offset:32
	global_load_dwordx2 v[224:225], v139, s[8:9]
	global_load_dwordx2 v[226:227], v139, s[8:9] offset:32
	global_load_dwordx2 v[228:229], v136, s[8:9] offset:256
	global_load_dwordx2 v[230:231], v136, s[8:9] offset:288
	global_load_dwordx2 v[232:233], v137, s[8:9] offset:256
	global_load_dwordx2 v[234:235], v137, s[8:9] offset:288
	global_load_dwordx2 v[236:237], v138, s[8:9] offset:256
	global_load_dwordx2 v[238:239], v138, s[8:9] offset:288
	global_load_dwordx2 v[240:241], v139, s[8:9] offset:256
	global_load_dwordx2 v[242:243], v139, s[8:9] offset:288
	s_waitcnt vmcnt(30)
	v_lshlrev_b32_e32 v140, 16, v181
	v_and_b32_e32 v141, 0xffff0000, v181
	v_and_b32_e32 v181, 0xffff0000, v180
	v_lshlrev_b32_e32 v180, 16, v180
	v_lshlrev_b32_e32 v142, 16, v183
	v_and_b32_e32 v143, 0xffff0000, v183
	v_and_b32_e32 v183, 0xffff0000, v182
	v_lshlrev_b32_e32 v182, 16, v182
	v_pk_fma_f32 v[124:125], v[180:181], s[30:31], v[124:125] op_sel_hi:[1,0,1]
	v_pk_fma_f32 v[126:127], v[140:141], s[30:31], v[126:127] op_sel_hi:[1,0,1]
	v_pk_fma_f32 v[120:121], v[182:183], s[30:31], v[120:121] op_sel_hi:[1,0,1]
	v_pk_fma_f32 v[122:123], v[142:143], s[30:31], v[122:123] op_sel_hi:[1,0,1]
	v_cvt_pk_bf16_f32 v124, v124, v125
	v_cvt_pk_bf16_f32 v125, v126, v127
	v_cvt_pk_bf16_f32 v120, v120, v121
	v_cvt_pk_bf16_f32 v121, v122, v123
	global_store_dwordx2 v132, v[124:125], s[6:7]
	global_store_dwordx2 v132, v[120:121], s[6:7] offset:32
	s_waitcnt vmcnt(30)
	v_lshlrev_b32_e32 v140, 16, v185
	v_and_b32_e32 v141, 0xffff0000, v185
	v_and_b32_e32 v185, 0xffff0000, v184
	v_lshlrev_b32_e32 v184, 16, v184
	v_lshlrev_b32_e32 v142, 16, v187
	v_and_b32_e32 v143, 0xffff0000, v187
	v_and_b32_e32 v187, 0xffff0000, v186
	v_lshlrev_b32_e32 v186, 16, v186
	v_pk_fma_f32 v[112:113], v[184:185], s[30:31], v[112:113] op_sel_hi:[1,0,1]
	v_pk_fma_f32 v[114:115], v[140:141], s[30:31], v[114:115] op_sel_hi:[1,0,1]
	v_pk_fma_f32 v[116:117], v[186:187], s[30:31], v[116:117] op_sel_hi:[1,0,1]
	v_pk_fma_f32 v[118:119], v[142:143], s[30:31], v[118:119] op_sel_hi:[1,0,1]
	v_cvt_pk_bf16_f32 v112, v112, v113
	v_cvt_pk_bf16_f32 v113, v114, v115
	v_cvt_pk_bf16_f32 v116, v116, v117
	v_cvt_pk_bf16_f32 v117, v118, v119
	global_store_dwordx2 v133, v[112:113], s[6:7]
	global_store_dwordx2 v133, v[116:117], s[6:7] offset:32
	s_waitcnt vmcnt(30)
	v_lshlrev_b32_e32 v140, 16, v189
	v_and_b32_e32 v141, 0xffff0000, v189
	v_and_b32_e32 v189, 0xffff0000, v188
	v_lshlrev_b32_e32 v188, 16, v188
	v_lshlrev_b32_e32 v142, 16, v191
	v_and_b32_e32 v143, 0xffff0000, v191
	v_and_b32_e32 v191, 0xffff0000, v190
	v_lshlrev_b32_e32 v190, 16, v190
	v_pk_fma_f32 v[104:105], v[188:189], s[30:31], v[104:105] op_sel_hi:[1,0,1]
	v_pk_fma_f32 v[106:107], v[140:141], s[30:31], v[106:107] op_sel_hi:[1,0,1]
	v_pk_fma_f32 v[108:109], v[190:191], s[30:31], v[108:109] op_sel_hi:[1,0,1]
	v_pk_fma_f32 v[110:111], v[142:143], s[30:31], v[110:111] op_sel_hi:[1,0,1]
	v_cvt_pk_bf16_f32 v104, v104, v105
	v_cvt_pk_bf16_f32 v105, v106, v107
	v_cvt_pk_bf16_f32 v108, v108, v109
	v_cvt_pk_bf16_f32 v109, v110, v111
	global_store_dwordx2 v134, v[104:105], s[6:7]
	global_store_dwordx2 v134, v[108:109], s[6:7] offset:32
	s_waitcnt vmcnt(30)
	v_lshlrev_b32_e32 v140, 16, v193
	v_and_b32_e32 v141, 0xffff0000, v193
	v_and_b32_e32 v193, 0xffff0000, v192
	v_lshlrev_b32_e32 v192, 16, v192
	v_lshlrev_b32_e32 v142, 16, v195
	v_and_b32_e32 v143, 0xffff0000, v195
	v_and_b32_e32 v195, 0xffff0000, v194
	v_lshlrev_b32_e32 v194, 16, v194
	v_pk_fma_f32 v[96:97], v[192:193], s[30:31], v[96:97] op_sel_hi:[1,0,1]
	v_pk_fma_f32 v[98:99], v[140:141], s[30:31], v[98:99] op_sel_hi:[1,0,1]
	v_pk_fma_f32 v[100:101], v[194:195], s[30:31], v[100:101] op_sel_hi:[1,0,1]
	v_pk_fma_f32 v[102:103], v[142:143], s[30:31], v[102:103] op_sel_hi:[1,0,1]
	v_cvt_pk_bf16_f32 v96, v96, v97
	v_cvt_pk_bf16_f32 v97, v98, v99
	v_cvt_pk_bf16_f32 v100, v100, v101
	v_cvt_pk_bf16_f32 v101, v102, v103
	global_store_dwordx2 v135, v[96:97], s[6:7]
	global_store_dwordx2 v135, v[100:101], s[6:7] offset:32
	s_waitcnt vmcnt(30)
	v_lshlrev_b32_e32 v140, 16, v197
	v_and_b32_e32 v141, 0xffff0000, v197
	v_and_b32_e32 v197, 0xffff0000, v196
	v_lshlrev_b32_e32 v196, 16, v196
	v_lshlrev_b32_e32 v142, 16, v199
	v_and_b32_e32 v143, 0xffff0000, v199
	v_and_b32_e32 v199, 0xffff0000, v198
	v_lshlrev_b32_e32 v198, 16, v198
	v_pk_fma_f32 v[92:93], v[196:197], s[30:31], v[92:93] op_sel_hi:[1,0,1]
	v_pk_fma_f32 v[94:95], v[140:141], s[30:31], v[94:95] op_sel_hi:[1,0,1]
	v_pk_fma_f32 v[88:89], v[198:199], s[30:31], v[88:89] op_sel_hi:[1,0,1]
	v_pk_fma_f32 v[90:91], v[142:143], s[30:31], v[90:91] op_sel_hi:[1,0,1]
	v_cvt_pk_bf16_f32 v92, v92, v93
	v_cvt_pk_bf16_f32 v93, v94, v95
	v_cvt_pk_bf16_f32 v88, v88, v89
	v_cvt_pk_bf16_f32 v89, v90, v91
	global_store_dwordx2 v132, v[92:93], s[6:7] offset:256
	global_store_dwordx2 v132, v[88:89], s[6:7] offset:288
	s_waitcnt vmcnt(30)
	v_lshlrev_b32_e32 v140, 16, v201
	v_and_b32_e32 v141, 0xffff0000, v201
	v_and_b32_e32 v201, 0xffff0000, v200
	v_lshlrev_b32_e32 v200, 16, v200
	v_lshlrev_b32_e32 v142, 16, v203
	v_and_b32_e32 v143, 0xffff0000, v203
	v_and_b32_e32 v203, 0xffff0000, v202
	v_lshlrev_b32_e32 v202, 16, v202
	v_pk_fma_f32 v[80:81], v[200:201], s[30:31], v[80:81] op_sel_hi:[1,0,1]
	v_pk_fma_f32 v[82:83], v[140:141], s[30:31], v[82:83] op_sel_hi:[1,0,1]
	v_pk_fma_f32 v[84:85], v[202:203], s[30:31], v[84:85] op_sel_hi:[1,0,1]
	v_pk_fma_f32 v[86:87], v[142:143], s[30:31], v[86:87] op_sel_hi:[1,0,1]
	v_cvt_pk_bf16_f32 v80, v80, v81
	v_cvt_pk_bf16_f32 v81, v82, v83
	v_cvt_pk_bf16_f32 v84, v84, v85
	v_cvt_pk_bf16_f32 v85, v86, v87
	global_store_dwordx2 v133, v[80:81], s[6:7] offset:256
	global_store_dwordx2 v133, v[84:85], s[6:7] offset:288
	s_waitcnt vmcnt(30)
	v_lshlrev_b32_e32 v140, 16, v205
	v_and_b32_e32 v141, 0xffff0000, v205
	v_and_b32_e32 v205, 0xffff0000, v204
	v_lshlrev_b32_e32 v204, 16, v204
	v_lshlrev_b32_e32 v142, 16, v207
	v_and_b32_e32 v143, 0xffff0000, v207
	v_and_b32_e32 v207, 0xffff0000, v206
	v_lshlrev_b32_e32 v206, 16, v206
	v_pk_fma_f32 v[72:73], v[204:205], s[30:31], v[72:73] op_sel_hi:[1,0,1]
	v_pk_fma_f32 v[74:75], v[140:141], s[30:31], v[74:75] op_sel_hi:[1,0,1]
	v_pk_fma_f32 v[76:77], v[206:207], s[30:31], v[76:77] op_sel_hi:[1,0,1]
	v_pk_fma_f32 v[78:79], v[142:143], s[30:31], v[78:79] op_sel_hi:[1,0,1]
	v_cvt_pk_bf16_f32 v72, v72, v73
	v_cvt_pk_bf16_f32 v73, v74, v75
	v_cvt_pk_bf16_f32 v76, v76, v77
	v_cvt_pk_bf16_f32 v77, v78, v79
	global_store_dwordx2 v134, v[72:73], s[6:7] offset:256
	global_store_dwordx2 v134, v[76:77], s[6:7] offset:288
	s_waitcnt vmcnt(30)
	v_lshlrev_b32_e32 v140, 16, v209
	v_and_b32_e32 v141, 0xffff0000, v209
	v_and_b32_e32 v209, 0xffff0000, v208
	v_lshlrev_b32_e32 v208, 16, v208
	v_lshlrev_b32_e32 v142, 16, v211
	v_and_b32_e32 v143, 0xffff0000, v211
	v_and_b32_e32 v211, 0xffff0000, v210
	v_lshlrev_b32_e32 v210, 16, v210
	v_pk_fma_f32 v[64:65], v[208:209], s[30:31], v[64:65] op_sel_hi:[1,0,1]
	v_pk_fma_f32 v[66:67], v[140:141], s[30:31], v[66:67] op_sel_hi:[1,0,1]
	v_pk_fma_f32 v[68:69], v[210:211], s[30:31], v[68:69] op_sel_hi:[1,0,1]
	v_pk_fma_f32 v[70:71], v[142:143], s[30:31], v[70:71] op_sel_hi:[1,0,1]
	v_cvt_pk_bf16_f32 v64, v64, v65
	v_cvt_pk_bf16_f32 v65, v66, v67
	v_cvt_pk_bf16_f32 v68, v68, v69
	v_cvt_pk_bf16_f32 v69, v70, v71
	global_store_dwordx2 v135, v[64:65], s[6:7] offset:256
	global_store_dwordx2 v135, v[68:69], s[6:7] offset:288
	s_waitcnt vmcnt(30)
	v_lshlrev_b32_e32 v140, 16, v213
	v_and_b32_e32 v141, 0xffff0000, v213
	v_and_b32_e32 v213, 0xffff0000, v212
	v_lshlrev_b32_e32 v212, 16, v212
	v_lshlrev_b32_e32 v142, 16, v215
	v_and_b32_e32 v143, 0xffff0000, v215
	v_and_b32_e32 v215, 0xffff0000, v214
	v_lshlrev_b32_e32 v214, 16, v214
	v_pk_fma_f32 v[60:61], v[212:213], s[30:31], v[60:61] op_sel_hi:[1,0,1]
	v_pk_fma_f32 v[62:63], v[140:141], s[30:31], v[62:63] op_sel_hi:[1,0,1]
	v_pk_fma_f32 v[56:57], v[214:215], s[30:31], v[56:57] op_sel_hi:[1,0,1]
	v_pk_fma_f32 v[58:59], v[142:143], s[30:31], v[58:59] op_sel_hi:[1,0,1]
	v_cvt_pk_bf16_f32 v60, v60, v61
	v_cvt_pk_bf16_f32 v61, v62, v63
	v_cvt_pk_bf16_f32 v56, v56, v57
	v_cvt_pk_bf16_f32 v57, v58, v59
	global_store_dwordx2 v136, v[60:61], s[6:7]
	global_store_dwordx2 v136, v[56:57], s[6:7] offset:32
	s_waitcnt vmcnt(30)
	v_lshlrev_b32_e32 v140, 16, v217
	v_and_b32_e32 v141, 0xffff0000, v217
	v_and_b32_e32 v217, 0xffff0000, v216
	v_lshlrev_b32_e32 v216, 16, v216
	v_lshlrev_b32_e32 v142, 16, v219
	v_and_b32_e32 v143, 0xffff0000, v219
	v_and_b32_e32 v219, 0xffff0000, v218
	v_lshlrev_b32_e32 v218, 16, v218
	v_pk_fma_f32 v[48:49], v[216:217], s[30:31], v[48:49] op_sel_hi:[1,0,1]
	v_pk_fma_f32 v[50:51], v[140:141], s[30:31], v[50:51] op_sel_hi:[1,0,1]
	v_pk_fma_f32 v[52:53], v[218:219], s[30:31], v[52:53] op_sel_hi:[1,0,1]
	v_pk_fma_f32 v[54:55], v[142:143], s[30:31], v[54:55] op_sel_hi:[1,0,1]
	v_cvt_pk_bf16_f32 v48, v48, v49
	v_cvt_pk_bf16_f32 v49, v50, v51
	v_cvt_pk_bf16_f32 v52, v52, v53
	v_cvt_pk_bf16_f32 v53, v54, v55
	global_store_dwordx2 v137, v[48:49], s[6:7]
	global_store_dwordx2 v137, v[52:53], s[6:7] offset:32
	s_waitcnt vmcnt(30)
	v_lshlrev_b32_e32 v140, 16, v221
	v_and_b32_e32 v141, 0xffff0000, v221
	v_and_b32_e32 v221, 0xffff0000, v220
	v_lshlrev_b32_e32 v220, 16, v220
	v_lshlrev_b32_e32 v142, 16, v223
	v_and_b32_e32 v143, 0xffff0000, v223
	v_and_b32_e32 v223, 0xffff0000, v222
	v_lshlrev_b32_e32 v222, 16, v222
	v_pk_fma_f32 v[40:41], v[220:221], s[30:31], v[40:41] op_sel_hi:[1,0,1]
	v_pk_fma_f32 v[42:43], v[140:141], s[30:31], v[42:43] op_sel_hi:[1,0,1]
	v_pk_fma_f32 v[44:45], v[222:223], s[30:31], v[44:45] op_sel_hi:[1,0,1]
	v_pk_fma_f32 v[46:47], v[142:143], s[30:31], v[46:47] op_sel_hi:[1,0,1]
	v_cvt_pk_bf16_f32 v40, v40, v41
	v_cvt_pk_bf16_f32 v41, v42, v43
	v_cvt_pk_bf16_f32 v44, v44, v45
	v_cvt_pk_bf16_f32 v45, v46, v47
	global_store_dwordx2 v138, v[40:41], s[6:7]
	global_store_dwordx2 v138, v[44:45], s[6:7] offset:32
	s_waitcnt vmcnt(30)
	v_lshlrev_b32_e32 v140, 16, v225
	v_and_b32_e32 v141, 0xffff0000, v225
	v_and_b32_e32 v225, 0xffff0000, v224
	v_lshlrev_b32_e32 v224, 16, v224
	v_lshlrev_b32_e32 v142, 16, v227
	v_and_b32_e32 v143, 0xffff0000, v227
	v_and_b32_e32 v227, 0xffff0000, v226
	v_lshlrev_b32_e32 v226, 16, v226
	v_pk_fma_f32 v[32:33], v[224:225], s[30:31], v[32:33] op_sel_hi:[1,0,1]
	v_pk_fma_f32 v[34:35], v[140:141], s[30:31], v[34:35] op_sel_hi:[1,0,1]
	v_pk_fma_f32 v[36:37], v[226:227], s[30:31], v[36:37] op_sel_hi:[1,0,1]
	v_pk_fma_f32 v[38:39], v[142:143], s[30:31], v[38:39] op_sel_hi:[1,0,1]
	v_cvt_pk_bf16_f32 v32, v32, v33
	v_cvt_pk_bf16_f32 v33, v34, v35
	v_cvt_pk_bf16_f32 v36, v36, v37
	v_cvt_pk_bf16_f32 v37, v38, v39
	global_store_dwordx2 v139, v[32:33], s[6:7]
	global_store_dwordx2 v139, v[36:37], s[6:7] offset:32
	s_waitcnt vmcnt(30)
	v_lshlrev_b32_e32 v140, 16, v229
	v_and_b32_e32 v141, 0xffff0000, v229
	v_and_b32_e32 v229, 0xffff0000, v228
	v_lshlrev_b32_e32 v228, 16, v228
	v_lshlrev_b32_e32 v142, 16, v231
	v_and_b32_e32 v143, 0xffff0000, v231
	v_and_b32_e32 v231, 0xffff0000, v230
	v_lshlrev_b32_e32 v230, 16, v230
	v_pk_fma_f32 v[28:29], v[228:229], s[30:31], v[28:29] op_sel_hi:[1,0,1]
	v_pk_fma_f32 v[30:31], v[140:141], s[30:31], v[30:31] op_sel_hi:[1,0,1]
	v_pk_fma_f32 v[24:25], v[230:231], s[30:31], v[24:25] op_sel_hi:[1,0,1]
	v_pk_fma_f32 v[26:27], v[142:143], s[30:31], v[26:27] op_sel_hi:[1,0,1]
	v_cvt_pk_bf16_f32 v28, v28, v29
	v_cvt_pk_bf16_f32 v29, v30, v31
	v_cvt_pk_bf16_f32 v24, v24, v25
	v_cvt_pk_bf16_f32 v25, v26, v27
	global_store_dwordx2 v136, v[28:29], s[6:7] offset:256
	global_store_dwordx2 v136, v[24:25], s[6:7] offset:288
	s_waitcnt vmcnt(30)
	v_lshlrev_b32_e32 v140, 16, v233
	v_and_b32_e32 v141, 0xffff0000, v233
	v_and_b32_e32 v233, 0xffff0000, v232
	v_lshlrev_b32_e32 v232, 16, v232
	v_lshlrev_b32_e32 v142, 16, v235
	v_and_b32_e32 v143, 0xffff0000, v235
	v_and_b32_e32 v235, 0xffff0000, v234
	v_lshlrev_b32_e32 v234, 16, v234
	v_pk_fma_f32 v[16:17], v[232:233], s[30:31], v[16:17] op_sel_hi:[1,0,1]
	v_pk_fma_f32 v[18:19], v[140:141], s[30:31], v[18:19] op_sel_hi:[1,0,1]
	v_pk_fma_f32 v[20:21], v[234:235], s[30:31], v[20:21] op_sel_hi:[1,0,1]
	v_pk_fma_f32 v[22:23], v[142:143], s[30:31], v[22:23] op_sel_hi:[1,0,1]
	v_cvt_pk_bf16_f32 v16, v16, v17
	v_cvt_pk_bf16_f32 v17, v18, v19
	v_cvt_pk_bf16_f32 v20, v20, v21
	v_cvt_pk_bf16_f32 v21, v22, v23
	global_store_dwordx2 v137, v[16:17], s[6:7] offset:256
	global_store_dwordx2 v137, v[20:21], s[6:7] offset:288
	s_waitcnt vmcnt(30)
	v_lshlrev_b32_e32 v140, 16, v237
	v_and_b32_e32 v141, 0xffff0000, v237
	v_and_b32_e32 v237, 0xffff0000, v236
	v_lshlrev_b32_e32 v236, 16, v236
	v_lshlrev_b32_e32 v142, 16, v239
	v_and_b32_e32 v143, 0xffff0000, v239
	v_and_b32_e32 v239, 0xffff0000, v238
	v_lshlrev_b32_e32 v238, 16, v238
	v_pk_fma_f32 v[8:9], v[236:237], s[30:31], v[8:9] op_sel_hi:[1,0,1]
	v_pk_fma_f32 v[10:11], v[140:141], s[30:31], v[10:11] op_sel_hi:[1,0,1]
	v_pk_fma_f32 v[12:13], v[238:239], s[30:31], v[12:13] op_sel_hi:[1,0,1]
	v_pk_fma_f32 v[14:15], v[142:143], s[30:31], v[14:15] op_sel_hi:[1,0,1]
	v_cvt_pk_bf16_f32 v8, v8, v9
	v_cvt_pk_bf16_f32 v9, v10, v11
	v_cvt_pk_bf16_f32 v12, v12, v13
	v_cvt_pk_bf16_f32 v13, v14, v15
	global_store_dwordx2 v138, v[8:9], s[6:7] offset:256
	global_store_dwordx2 v138, v[12:13], s[6:7] offset:288
	s_waitcnt vmcnt(30)
	v_lshlrev_b32_e32 v140, 16, v241
	v_and_b32_e32 v141, 0xffff0000, v241
	v_and_b32_e32 v241, 0xffff0000, v240
	v_lshlrev_b32_e32 v240, 16, v240
	v_lshlrev_b32_e32 v142, 16, v243
	v_and_b32_e32 v143, 0xffff0000, v243
	v_and_b32_e32 v243, 0xffff0000, v242
	v_lshlrev_b32_e32 v242, 16, v242
	v_pk_fma_f32 v[0:1], v[240:241], s[30:31], v[0:1] op_sel_hi:[1,0,1]
	v_pk_fma_f32 v[2:3], v[140:141], s[30:31], v[2:3] op_sel_hi:[1,0,1]
	v_pk_fma_f32 v[4:5], v[242:243], s[30:31], v[4:5] op_sel_hi:[1,0,1]
	v_pk_fma_f32 v[6:7], v[142:143], s[30:31], v[6:7] op_sel_hi:[1,0,1]
	v_cvt_pk_bf16_f32 v0, v0, v1
	v_cvt_pk_bf16_f32 v1, v2, v3
	v_cvt_pk_bf16_f32 v4, v4, v5
	v_cvt_pk_bf16_f32 v5, v6, v7
	global_store_dwordx2 v139, v[0:1], s[6:7] offset:256
	global_store_dwordx2 v139, v[4:5], s[6:7] offset:288
	s_andn2_b64 vcc, exec, s[0:1]
	s_mov_b32 s40, s56
	s_mov_b32 s42, s57
	s_cbranch_vccz .LBB0_1872
